# nt policy also on the once-read loads of the P4 scan (chunk states) and P9 final norm (x2)
# speedup vs baseline: 1.0170x; 1.0011x over previous
; __device__ __forceinline__ void unpack8(u32x4 r, float* f) { f[0] = bflo(r.x); f[1] = bfhi(r.x); f[2] = bflo(r.y); f[3] = bfhi(r.y); f[4] = bflo(r.z); f[5] = bfhi(r.z); f[6] = bflo(r.w); f[7] = bfhi(r.w); }
; __device__ __forceinline__ u32x4 pack8(const float* f) { u32x4 o; o.x = pk2(f[0], f[1]); o.y = pk2(f[2], f[3]); o.z = pk2(f[4], f[5]); o.w = pk2(f[6], f[7]); return o; }
;     __device__ __forceinline__ PT() { out = (float*)(__attribute__((address_space(1))) float*)ptab_get(23); ws = (unsigned char*)(__attribute__((address_space(1))) unsigned char*)ptab_get(24); }
; __device__ __forceinline__ void phase_scan(const PT& p, int tid) {
;     unsigned char* ws = p.ws; const bf16* ST = (const bf16*)(ws + WS_STATES); const float* CD = (const float*)(ws + WS_CD); bf16* PV = (bf16*)((unsigned char*)p.out + DO_PREV);
;     for (int id = blockIdx.x * 512 + tid; id < NBATCH * 32 * 64 * 16; id += gridDim.x * 512) {
;         const int b = id >> 15, rem = id & 32767, hh = rem >> 10;
;         float run[8];
; #pragma unroll
;         for (int j = 0; j < 8; ++j) run[j] = 0.f;
; #pragma unroll
;         for (int c = 0; c < 16; ++c) {
;             const size_t off = ((size_t)(b * 16 + c) * 32 * 64 * 16 + rem) * 8;
;             *(u32x4*)(PV + off) = pack8(run);
;             if (c < 15) { float s[8]; unpack8(*(const u32x4*)(ST + off), s); const float cd = CD[(b * 16 + c) * 32 + hh];
; #pragma unroll
;                 for (int j = 0; j < 8; ++j) run[j] = run[j] * cd + s[j]; }
;         }
;     }
.LBB0_427:
	s_or_b64 exec, exec, s[0:1]
	s_waitcnt lgkmcnt(0)
	v_mov_b32_e32 v0, 0x23eb8
	s_barrier
	ds_read_b64 v[0:1], v0
	v_mov_b32_e32 v2, 0x23ec0
	ds_read_b64 v[2:3], v2
	s_mov_b32 s2, 0x40000
	s_waitcnt lgkmcnt(1)
	v_readfirstlane_b32 s0, v0
	v_mov_b32_e32 v0, v196
	v_readfirstlane_b32 s1, v1
	v_add_u32_e32 v16, s51, v0
	s_waitcnt lgkmcnt(0)
	v_readfirstlane_b32 s7, v3
	v_readfirstlane_b32 s6, v2
	v_cmp_gt_i32_e32 vcc, s2, v16
	s_and_saveexec_b64 s[2:3], vcc
	s_cbranch_execz .LBB0_430
	s_add_u32 s4, s6, 0x12900000
	s_addc_u32 s5, s7, 0
	s_add_u32 s6, s6, 0x40000
	s_addc_u32 s7, s7, 0
	v_ashrrev_i32_e32 v2, 15, v16
	v_and_b32_e32 v0, 0x7fff, v16
	v_lshlrev_b32_e32 v0, 4, v0
	v_lshl_or_b32 v0, v2, 23, v0
	v_bfe_u32 v1, v16, 10, 5
	v_lshl_or_b32 v1, v2, 9, v1
	v_lshlrev_b32_e32 v1, 2, v1
	v_add_u32_e32 v2, 0x2000, v1
	v_mov_b32_e32 v3, v0
	global_load_dwordx4 v[20:23], v3, s[4:5] nt
	global_load_dword v80, v1, s[6:7]
	v_add_u32_e32 v95, 0x80000, v0
	global_load_dwordx4 v[24:27], v95, s[4:5] nt
	global_load_dword v81, v1, s[6:7] offset:128
	v_add_u32_e32 v3, 0x100000, v0
	global_load_dwordx4 v[28:31], v3, s[4:5] nt
	global_load_dword v82, v1, s[6:7] offset:256
	v_add_u32_e32 v95, 0x180000, v0
	global_load_dwordx4 v[32:35], v95, s[4:5] nt
	global_load_dword v83, v1, s[6:7] offset:384
	v_add_u32_e32 v3, 0x200000, v0
	global_load_dwordx4 v[36:39], v3, s[4:5] nt
	global_load_dword v84, v1, s[6:7] offset:512
	v_add_u32_e32 v95, 0x280000, v0
	global_load_dwordx4 v[40:43], v95, s[4:5] nt
	global_load_dword v85, v1, s[6:7] offset:640
	v_add_u32_e32 v3, 0x300000, v0
	global_load_dwordx4 v[44:47], v3, s[4:5] nt
	global_load_dword v86, v1, s[6:7] offset:768
	v_add_u32_e32 v95, 0x380000, v0
	global_load_dwordx4 v[48:51], v95, s[4:5] nt
	global_load_dword v87, v1, s[6:7] offset:896
	v_add_u32_e32 v3, 0x400000, v0
	global_load_dwordx4 v[52:55], v3, s[4:5] nt
	global_load_dword v88, v1, s[6:7] offset:1024
	v_add_u32_e32 v95, 0x480000, v0
	global_load_dwordx4 v[56:59], v95, s[4:5] nt
	global_load_dword v89, v1, s[6:7] offset:1152
	v_add_u32_e32 v3, 0x500000, v0
	global_load_dwordx4 v[60:63], v3, s[4:5] nt
	global_load_dword v90, v1, s[6:7] offset:1280
	v_add_u32_e32 v95, 0x580000, v0
	global_load_dwordx4 v[64:67], v95, s[4:5] nt
	global_load_dword v91, v1, s[6:7] offset:1408
	v_add_u32_e32 v3, 0x600000, v0
	global_load_dwordx4 v[68:71], v3, s[4:5] nt
	global_load_dword v92, v1, s[6:7] offset:1536
	v_add_u32_e32 v95, 0x680000, v0
	global_load_dwordx4 v[72:75], v95, s[4:5] nt
	global_load_dword v93, v1, s[6:7] offset:1664
	v_add_u32_e32 v3, 0x700000, v0
	global_load_dwordx4 v[76:79], v3, s[4:5] nt
	global_load_dword v94, v1, s[6:7] offset:1792
	v_add_u32_e32 v95, 0x2000000, v0
	global_load_dwordx4 v[96:99], v95, s[4:5] nt
	global_load_dword v156, v2, s[6:7]
	v_add_u32_e32 v3, 0x2080000, v0
	global_load_dwordx4 v[100:103], v3, s[4:5] nt
	global_load_dword v157, v2, s[6:7] offset:128
	v_add_u32_e32 v95, 0x2100000, v0
	global_load_dwordx4 v[104:107], v95, s[4:5] nt
	global_load_dword v158, v2, s[6:7] offset:256
	v_add_u32_e32 v3, 0x2180000, v0
	global_load_dwordx4 v[108:111], v3, s[4:5] nt
	global_load_dword v159, v2, s[6:7] offset:384
	v_add_u32_e32 v95, 0x2200000, v0
	global_load_dwordx4 v[112:115], v95, s[4:5] nt
	global_load_dword v160, v2, s[6:7] offset:512
	v_add_u32_e32 v3, 0x2280000, v0
	global_load_dwordx4 v[116:119], v3, s[4:5] nt
	global_load_dword v161, v2, s[6:7] offset:640
	v_add_u32_e32 v95, 0x2300000, v0
	global_load_dwordx4 v[120:123], v95, s[4:5] nt
	global_load_dword v162, v2, s[6:7] offset:768
	v_add_u32_e32 v3, 0x2380000, v0
	global_load_dwordx4 v[124:127], v3, s[4:5] nt
	global_load_dword v163, v2, s[6:7] offset:896
	v_add_u32_e32 v95, 0x2400000, v0
	global_load_dwordx4 v[128:131], v95, s[4:5] nt
	global_load_dword v164, v2, s[6:7] offset:1024
	v_add_u32_e32 v3, 0x2480000, v0
	global_load_dwordx4 v[132:135], v3, s[4:5] nt
	global_load_dword v165, v2, s[6:7] offset:1152
	v_add_u32_e32 v95, 0x2500000, v0
	global_load_dwordx4 v[136:139], v95, s[4:5] nt
	global_load_dword v166, v2, s[6:7] offset:1280
	v_add_u32_e32 v3, 0x2580000, v0
	global_load_dwordx4 v[140:143], v3, s[4:5] nt
	global_load_dword v167, v2, s[6:7] offset:1408
	v_add_u32_e32 v95, 0x2600000, v0
	global_load_dwordx4 v[144:147], v95, s[4:5] nt
	global_load_dword v168, v2, s[6:7] offset:1536
	v_add_u32_e32 v3, 0x2680000, v0
	global_load_dwordx4 v[148:151], v3, s[4:5] nt
	global_load_dword v169, v2, s[6:7] offset:1664
	v_add_u32_e32 v95, 0x2700000, v0
	global_load_dwordx4 v[152:155], v95, s[4:5] nt
	global_load_dword v170, v2, s[6:7] offset:1792
	v_mov_b32_e32 v4, 0
	v_mov_b32_e32 v5, 0
	v_mov_b32_e32 v6, 0
	v_mov_b32_e32 v7, 0
	v_mov_b32_e32 v8, 0
	v_mov_b32_e32 v9, 0
	v_mov_b32_e32 v10, 0
	v_mov_b32_e32 v11, 0
	v_cvt_pk_bf16_f32 v16, v4, v5
	v_cvt_pk_bf16_f32 v17, v6, v7
	v_cvt_pk_bf16_f32 v18, v8, v9
	v_cvt_pk_bf16_f32 v19, v10, v11
	v_mov_b32_e32 v3, v0
	global_store_dwordx4 v3, v[16:19], s[0:1]
	s_waitcnt vmcnt(59)
	v_lshlrev_b32_e32 v12, 16, v20
	v_and_b32_e32 v20, 0xffff0000, v20
	v_lshlrev_b32_e32 v13, 16, v21
	v_and_b32_e32 v21, 0xffff0000, v21
	v_lshlrev_b32_e32 v14, 16, v22
	v_and_b32_e32 v22, 0xffff0000, v22
	v_lshlrev_b32_e32 v15, 16, v23
	v_and_b32_e32 v23, 0xffff0000, v23
	v_fma_f32 v4, v80, v4, v12
	v_fma_f32 v5, v80, v5, v20
	v_fma_f32 v6, v80, v6, v13
	v_fma_f32 v7, v80, v7, v21
	v_fma_f32 v8, v80, v8, v14
	v_fma_f32 v9, v80, v9, v22
	v_fma_f32 v10, v80, v10, v15
	v_fma_f32 v11, v80, v11, v23
	v_cvt_pk_bf16_f32 v172, v4, v5
	v_cvt_pk_bf16_f32 v173, v6, v7
	v_cvt_pk_bf16_f32 v174, v8, v9
	v_cvt_pk_bf16_f32 v175, v10, v11
	v_add_u32_e32 v95, 0x80000, v0
	global_store_dwordx4 v95, v[172:175], s[0:1]
	s_waitcnt vmcnt(58)
; __device__ __forceinline__ void unpack8(u32x4 r, float* f) { f[0] = bflo(r.x); f[1] = bfhi(r.x); f[2] = bflo(r.y); f[3] = bfhi(r.y); f[4] = bflo(r.z); f[5] = bfhi(r.z); f[6] = bflo(r.w); f[7] = bfhi(r.w); }
; __device__ __forceinline__ u32x4 pack8(const float* f) { u32x4 o; o.x = pk2(f[0], f[1]); o.y = pk2(f[2], f[3]); o.z = pk2(f[4], f[5]); o.w = pk2(f[6], f[7]); return o; }
; __device__ __forceinline__ void phase_scan(const PT& p, int tid) {
;     ...
;         for (int c = 0; c < 16; ++c) {
;             const size_t off = ((size_t)(b * 16 + c) * 32 * 64 * 16 + rem) * 8;
;             *(u32x4*)(PV + off) = pack8(run);
;             if (c < 15) { float s[8]; unpack8(*(const u32x4*)(ST + off), s); const float cd = CD[(b * 16 + c) * 32 + hh];
; #pragma unroll
;                 for (int j = 0; j < 8; ++j) run[j] = run[j] * cd + s[j]; }
	v_lshlrev_b32_e32 v12, 16, v24
	v_and_b32_e32 v24, 0xffff0000, v24
	v_lshlrev_b32_e32 v13, 16, v25
	v_and_b32_e32 v25, 0xffff0000, v25
	v_lshlrev_b32_e32 v14, 16, v26
	v_and_b32_e32 v26, 0xffff0000, v26
	v_lshlrev_b32_e32 v15, 16, v27
	v_and_b32_e32 v27, 0xffff0000, v27
	v_fma_f32 v4, v81, v4, v12
	v_fma_f32 v5, v81, v5, v24
	v_fma_f32 v6, v81, v6, v13
	v_fma_f32 v7, v81, v7, v25
	v_fma_f32 v8, v81, v8, v14
	v_fma_f32 v9, v81, v9, v26
	v_fma_f32 v10, v81, v10, v15
	v_fma_f32 v11, v81, v11, v27
	v_cvt_pk_bf16_f32 v16, v4, v5
	v_cvt_pk_bf16_f32 v17, v6, v7
	v_cvt_pk_bf16_f32 v18, v8, v9
	v_cvt_pk_bf16_f32 v19, v10, v11
	v_add_u32_e32 v3, 0x100000, v0
	global_store_dwordx4 v3, v[16:19], s[0:1]
	s_waitcnt vmcnt(57)
	v_lshlrev_b32_e32 v12, 16, v28
	v_and_b32_e32 v28, 0xffff0000, v28
	v_lshlrev_b32_e32 v13, 16, v29
	v_and_b32_e32 v29, 0xffff0000, v29
	v_lshlrev_b32_e32 v14, 16, v30
	v_and_b32_e32 v30, 0xffff0000, v30
	v_lshlrev_b32_e32 v15, 16, v31
	v_and_b32_e32 v31, 0xffff0000, v31
	v_fma_f32 v4, v82, v4, v12
	v_fma_f32 v5, v82, v5, v28
	v_fma_f32 v6, v82, v6, v13
	v_fma_f32 v7, v82, v7, v29
	v_fma_f32 v8, v82, v8, v14
	v_fma_f32 v9, v82, v9, v30
	v_fma_f32 v10, v82, v10, v15
	v_fma_f32 v11, v82, v11, v31
	v_cvt_pk_bf16_f32 v172, v4, v5
	v_cvt_pk_bf16_f32 v173, v6, v7
	v_cvt_pk_bf16_f32 v174, v8, v9
	v_cvt_pk_bf16_f32 v175, v10, v11
	v_add_u32_e32 v95, 0x180000, v0
	global_store_dwordx4 v95, v[172:175], s[0:1]
	s_waitcnt vmcnt(56)
	v_lshlrev_b32_e32 v12, 16, v32
	v_and_b32_e32 v32, 0xffff0000, v32
	v_lshlrev_b32_e32 v13, 16, v33
	v_and_b32_e32 v33, 0xffff0000, v33
	v_lshlrev_b32_e32 v14, 16, v34
	v_and_b32_e32 v34, 0xffff0000, v34
	v_lshlrev_b32_e32 v15, 16, v35
	v_and_b32_e32 v35, 0xffff0000, v35
	v_fma_f32 v4, v83, v4, v12
	v_fma_f32 v5, v83, v5, v32
	v_fma_f32 v6, v83, v6, v13
	v_fma_f32 v7, v83, v7, v33
	v_fma_f32 v8, v83, v8, v14
	v_fma_f32 v9, v83, v9, v34
	v_fma_f32 v10, v83, v10, v15
	v_fma_f32 v11, v83, v11, v35
	v_cvt_pk_bf16_f32 v16, v4, v5
	v_cvt_pk_bf16_f32 v17, v6, v7
	v_cvt_pk_bf16_f32 v18, v8, v9
	v_cvt_pk_bf16_f32 v19, v10, v11
	v_add_u32_e32 v3, 0x200000, v0
	global_store_dwordx4 v3, v[16:19], s[0:1]
	s_waitcnt vmcnt(55)
	v_lshlrev_b32_e32 v12, 16, v36
	v_and_b32_e32 v36, 0xffff0000, v36
	v_lshlrev_b32_e32 v13, 16, v37
	v_and_b32_e32 v37, 0xffff0000, v37
	v_lshlrev_b32_e32 v14, 16, v38
	v_and_b32_e32 v38, 0xffff0000, v38
	v_lshlrev_b32_e32 v15, 16, v39
	v_and_b32_e32 v39, 0xffff0000, v39
	v_fma_f32 v4, v84, v4, v12
	v_fma_f32 v5, v84, v5, v36
	v_fma_f32 v6, v84, v6, v13
	v_fma_f32 v7, v84, v7, v37
	v_fma_f32 v8, v84, v8, v14
	v_fma_f32 v9, v84, v9, v38
	v_fma_f32 v10, v84, v10, v15
	v_fma_f32 v11, v84, v11, v39
	v_cvt_pk_bf16_f32 v172, v4, v5
	v_cvt_pk_bf16_f32 v173, v6, v7
	v_cvt_pk_bf16_f32 v174, v8, v9
	v_cvt_pk_bf16_f32 v175, v10, v11
	v_add_u32_e32 v95, 0x280000, v0
	global_store_dwordx4 v95, v[172:175], s[0:1]
	s_waitcnt vmcnt(54)
	v_lshlrev_b32_e32 v12, 16, v40
	v_and_b32_e32 v40, 0xffff0000, v40
	v_lshlrev_b32_e32 v13, 16, v41
	v_and_b32_e32 v41, 0xffff0000, v41
	v_lshlrev_b32_e32 v14, 16, v42
	v_and_b32_e32 v42, 0xffff0000, v42
	v_lshlrev_b32_e32 v15, 16, v43
	v_and_b32_e32 v43, 0xffff0000, v43
	v_fma_f32 v4, v85, v4, v12
	v_fma_f32 v5, v85, v5, v40
	v_fma_f32 v6, v85, v6, v13
	v_fma_f32 v7, v85, v7, v41
	v_fma_f32 v8, v85, v8, v14
	v_fma_f32 v9, v85, v9, v42
	v_fma_f32 v10, v85, v10, v15
	v_fma_f32 v11, v85, v11, v43
	v_cvt_pk_bf16_f32 v16, v4, v5
	v_cvt_pk_bf16_f32 v17, v6, v7
	v_cvt_pk_bf16_f32 v18, v8, v9
	v_cvt_pk_bf16_f32 v19, v10, v11
	v_add_u32_e32 v3, 0x300000, v0
	global_store_dwordx4 v3, v[16:19], s[0:1]
	s_waitcnt vmcnt(53)
	v_lshlrev_b32_e32 v12, 16, v44
	v_and_b32_e32 v44, 0xffff0000, v44
	v_lshlrev_b32_e32 v13, 16, v45
	v_and_b32_e32 v45, 0xffff0000, v45
	v_lshlrev_b32_e32 v14, 16, v46
	v_and_b32_e32 v46, 0xffff0000, v46
	v_lshlrev_b32_e32 v15, 16, v47
	v_and_b32_e32 v47, 0xffff0000, v47
	v_fma_f32 v4, v86, v4, v12
	v_fma_f32 v5, v86, v5, v44
	v_fma_f32 v6, v86, v6, v13
	v_fma_f32 v7, v86, v7, v45
	v_fma_f32 v8, v86, v8, v14
	v_fma_f32 v9, v86, v9, v46
	v_fma_f32 v10, v86, v10, v15
	v_fma_f32 v11, v86, v11, v47
	v_cvt_pk_bf16_f32 v172, v4, v5
	v_cvt_pk_bf16_f32 v173, v6, v7
	v_cvt_pk_bf16_f32 v174, v8, v9
	v_cvt_pk_bf16_f32 v175, v10, v11
	v_add_u32_e32 v95, 0x380000, v0
	global_store_dwordx4 v95, v[172:175], s[0:1]
	s_waitcnt vmcnt(52)
	v_lshlrev_b32_e32 v12, 16, v48
	v_and_b32_e32 v48, 0xffff0000, v48
	v_lshlrev_b32_e32 v13, 16, v49
	v_and_b32_e32 v49, 0xffff0000, v49
	v_lshlrev_b32_e32 v14, 16, v50
	v_and_b32_e32 v50, 0xffff0000, v50
	v_lshlrev_b32_e32 v15, 16, v51
	v_and_b32_e32 v51, 0xffff0000, v51
	v_fma_f32 v4, v87, v4, v12
	v_fma_f32 v5, v87, v5, v48
	v_fma_f32 v6, v87, v6, v13
	v_fma_f32 v7, v87, v7, v49
	v_fma_f32 v8, v87, v8, v14
	v_fma_f32 v9, v87, v9, v50
	v_fma_f32 v10, v87, v10, v15
	v_fma_f32 v11, v87, v11, v51
	v_cvt_pk_bf16_f32 v16, v4, v5
	v_cvt_pk_bf16_f32 v17, v6, v7
	v_cvt_pk_bf16_f32 v18, v8, v9
	v_cvt_pk_bf16_f32 v19, v10, v11
	v_add_u32_e32 v3, 0x400000, v0
	global_store_dwordx4 v3, v[16:19], s[0:1]
	s_waitcnt vmcnt(51)
	v_lshlrev_b32_e32 v12, 16, v52
	v_and_b32_e32 v52, 0xffff0000, v52
	v_lshlrev_b32_e32 v13, 16, v53
	v_and_b32_e32 v53, 0xffff0000, v53
	v_lshlrev_b32_e32 v14, 16, v54
	v_and_b32_e32 v54, 0xffff0000, v54
	v_lshlrev_b32_e32 v15, 16, v55
	v_and_b32_e32 v55, 0xffff0000, v55
	v_fma_f32 v4, v88, v4, v12
	v_fma_f32 v5, v88, v5, v52
	v_fma_f32 v6, v88, v6, v13
	v_fma_f32 v7, v88, v7, v53
	v_fma_f32 v8, v88, v8, v14
	v_fma_f32 v9, v88, v9, v54
	v_fma_f32 v10, v88, v10, v15
	v_fma_f32 v11, v88, v11, v55
	v_cvt_pk_bf16_f32 v172, v4, v5
	v_cvt_pk_bf16_f32 v173, v6, v7
	v_cvt_pk_bf16_f32 v174, v8, v9
	v_cvt_pk_bf16_f32 v175, v10, v11
	v_add_u32_e32 v95, 0x480000, v0
	global_store_dwordx4 v95, v[172:175], s[0:1]
	s_waitcnt vmcnt(50)
; __device__ __forceinline__ void unpack8(u32x4 r, float* f) { f[0] = bflo(r.x); f[1] = bfhi(r.x); f[2] = bflo(r.y); f[3] = bfhi(r.y); f[4] = bflo(r.z); f[5] = bfhi(r.z); f[6] = bflo(r.w); f[7] = bfhi(r.w); }
; __device__ __forceinline__ u32x4 pack8(const float* f) { u32x4 o; o.x = pk2(f[0], f[1]); o.y = pk2(f[2], f[3]); o.z = pk2(f[4], f[5]); o.w = pk2(f[6], f[7]); return o; }
; __device__ __forceinline__ void phase_scan(const PT& p, int tid) {
;     ...
;         for (int j = 0; j < 8; ++j) run[j] = 0.f;
; #pragma unroll
;         for (int c = 0; c < 16; ++c) {
;             const size_t off = ((size_t)(b * 16 + c) * 32 * 64 * 16 + rem) * 8;
;             *(u32x4*)(PV + off) = pack8(run);
;             if (c < 15) { float s[8]; unpack8(*(const u32x4*)(ST + off), s); const float cd = CD[(b * 16 + c) * 32 + hh];
; #pragma unroll
;                 for (int j = 0; j < 8; ++j) run[j] = run[j] * cd + s[j]; }
	v_lshlrev_b32_e32 v12, 16, v56
	v_and_b32_e32 v56, 0xffff0000, v56
	v_lshlrev_b32_e32 v13, 16, v57
	v_and_b32_e32 v57, 0xffff0000, v57
	v_lshlrev_b32_e32 v14, 16, v58
	v_and_b32_e32 v58, 0xffff0000, v58
	v_lshlrev_b32_e32 v15, 16, v59
	v_and_b32_e32 v59, 0xffff0000, v59
	v_fma_f32 v4, v89, v4, v12
	v_fma_f32 v5, v89, v5, v56
	v_fma_f32 v6, v89, v6, v13
	v_fma_f32 v7, v89, v7, v57
	v_fma_f32 v8, v89, v8, v14
	v_fma_f32 v9, v89, v9, v58
	v_fma_f32 v10, v89, v10, v15
	v_fma_f32 v11, v89, v11, v59
	v_cvt_pk_bf16_f32 v16, v4, v5
	v_cvt_pk_bf16_f32 v17, v6, v7
	v_cvt_pk_bf16_f32 v18, v8, v9
	v_cvt_pk_bf16_f32 v19, v10, v11
	v_add_u32_e32 v3, 0x500000, v0
	global_store_dwordx4 v3, v[16:19], s[0:1]
	s_waitcnt vmcnt(49)
	v_lshlrev_b32_e32 v12, 16, v60
	v_and_b32_e32 v60, 0xffff0000, v60
	v_lshlrev_b32_e32 v13, 16, v61
	v_and_b32_e32 v61, 0xffff0000, v61
	v_lshlrev_b32_e32 v14, 16, v62
	v_and_b32_e32 v62, 0xffff0000, v62
	v_lshlrev_b32_e32 v15, 16, v63
	v_and_b32_e32 v63, 0xffff0000, v63
	v_fma_f32 v4, v90, v4, v12
	v_fma_f32 v5, v90, v5, v60
	v_fma_f32 v6, v90, v6, v13
	v_fma_f32 v7, v90, v7, v61
	v_fma_f32 v8, v90, v8, v14
	v_fma_f32 v9, v90, v9, v62
	v_fma_f32 v10, v90, v10, v15
	v_fma_f32 v11, v90, v11, v63
	v_cvt_pk_bf16_f32 v172, v4, v5
	v_cvt_pk_bf16_f32 v173, v6, v7
	v_cvt_pk_bf16_f32 v174, v8, v9
	v_cvt_pk_bf16_f32 v175, v10, v11
	v_add_u32_e32 v95, 0x580000, v0
	global_store_dwordx4 v95, v[172:175], s[0:1]
	s_waitcnt vmcnt(48)
	v_lshlrev_b32_e32 v12, 16, v64
	v_and_b32_e32 v64, 0xffff0000, v64
	v_lshlrev_b32_e32 v13, 16, v65
	v_and_b32_e32 v65, 0xffff0000, v65
	v_lshlrev_b32_e32 v14, 16, v66
	v_and_b32_e32 v66, 0xffff0000, v66
	v_lshlrev_b32_e32 v15, 16, v67
	v_and_b32_e32 v67, 0xffff0000, v67
	v_fma_f32 v4, v91, v4, v12
	v_fma_f32 v5, v91, v5, v64
	v_fma_f32 v6, v91, v6, v13
	v_fma_f32 v7, v91, v7, v65
	v_fma_f32 v8, v91, v8, v14
	v_fma_f32 v9, v91, v9, v66
	v_fma_f32 v10, v91, v10, v15
	v_fma_f32 v11, v91, v11, v67
	v_cvt_pk_bf16_f32 v16, v4, v5
	v_cvt_pk_bf16_f32 v17, v6, v7
	v_cvt_pk_bf16_f32 v18, v8, v9
	v_cvt_pk_bf16_f32 v19, v10, v11
	v_add_u32_e32 v3, 0x600000, v0
	global_store_dwordx4 v3, v[16:19], s[0:1]
	s_waitcnt vmcnt(47)
	v_lshlrev_b32_e32 v12, 16, v68
	v_and_b32_e32 v68, 0xffff0000, v68
	v_lshlrev_b32_e32 v13, 16, v69
	v_and_b32_e32 v69, 0xffff0000, v69
	v_lshlrev_b32_e32 v14, 16, v70
	v_and_b32_e32 v70, 0xffff0000, v70
	v_lshlrev_b32_e32 v15, 16, v71
	v_and_b32_e32 v71, 0xffff0000, v71
	v_fma_f32 v4, v92, v4, v12
	v_fma_f32 v5, v92, v5, v68
	v_fma_f32 v6, v92, v6, v13
	v_fma_f32 v7, v92, v7, v69
	v_fma_f32 v8, v92, v8, v14
	v_fma_f32 v9, v92, v9, v70
	v_fma_f32 v10, v92, v10, v15
	v_fma_f32 v11, v92, v11, v71
	v_cvt_pk_bf16_f32 v172, v4, v5
	v_cvt_pk_bf16_f32 v173, v6, v7
	v_cvt_pk_bf16_f32 v174, v8, v9
	v_cvt_pk_bf16_f32 v175, v10, v11
	v_add_u32_e32 v95, 0x680000, v0
	global_store_dwordx4 v95, v[172:175], s[0:1]
	s_waitcnt vmcnt(46)
	v_lshlrev_b32_e32 v12, 16, v72
	v_and_b32_e32 v72, 0xffff0000, v72
	v_lshlrev_b32_e32 v13, 16, v73
	v_and_b32_e32 v73, 0xffff0000, v73
	v_lshlrev_b32_e32 v14, 16, v74
	v_and_b32_e32 v74, 0xffff0000, v74
	v_lshlrev_b32_e32 v15, 16, v75
	v_and_b32_e32 v75, 0xffff0000, v75
	v_fma_f32 v4, v93, v4, v12
	v_fma_f32 v5, v93, v5, v72
	v_fma_f32 v6, v93, v6, v13
	v_fma_f32 v7, v93, v7, v73
	v_fma_f32 v8, v93, v8, v14
	v_fma_f32 v9, v93, v9, v74
	v_fma_f32 v10, v93, v10, v15
	v_fma_f32 v11, v93, v11, v75
	v_cvt_pk_bf16_f32 v16, v4, v5
	v_cvt_pk_bf16_f32 v17, v6, v7
	v_cvt_pk_bf16_f32 v18, v8, v9
	v_cvt_pk_bf16_f32 v19, v10, v11
	v_add_u32_e32 v3, 0x700000, v0
	global_store_dwordx4 v3, v[16:19], s[0:1]
	s_waitcnt vmcnt(45)
	v_lshlrev_b32_e32 v12, 16, v76
	v_and_b32_e32 v76, 0xffff0000, v76
	v_lshlrev_b32_e32 v13, 16, v77
	v_and_b32_e32 v77, 0xffff0000, v77
	v_lshlrev_b32_e32 v14, 16, v78
	v_and_b32_e32 v78, 0xffff0000, v78
	v_lshlrev_b32_e32 v15, 16, v79
	v_and_b32_e32 v79, 0xffff0000, v79
	v_fma_f32 v4, v94, v4, v12
	v_fma_f32 v5, v94, v5, v76
	v_fma_f32 v6, v94, v6, v13
	v_fma_f32 v7, v94, v7, v77
	v_fma_f32 v8, v94, v8, v14
	v_fma_f32 v9, v94, v9, v78
	v_fma_f32 v10, v94, v10, v15
	v_fma_f32 v11, v94, v11, v79
	v_cvt_pk_bf16_f32 v172, v4, v5
	v_cvt_pk_bf16_f32 v173, v6, v7
	v_cvt_pk_bf16_f32 v174, v8, v9
	v_cvt_pk_bf16_f32 v175, v10, v11
	v_add_u32_e32 v95, 0x780000, v0
	global_store_dwordx4 v95, v[172:175], s[0:1]
	v_mov_b32_e32 v4, 0
	v_mov_b32_e32 v5, 0
	v_mov_b32_e32 v6, 0
	v_mov_b32_e32 v7, 0
	v_mov_b32_e32 v8, 0
	v_mov_b32_e32 v9, 0
	v_mov_b32_e32 v10, 0
	v_mov_b32_e32 v11, 0
	v_cvt_pk_bf16_f32 v16, v4, v5
	v_cvt_pk_bf16_f32 v17, v6, v7
	v_cvt_pk_bf16_f32 v18, v8, v9
	v_cvt_pk_bf16_f32 v19, v10, v11
	v_add_u32_e32 v3, 0x2000000, v0
	global_store_dwordx4 v3, v[16:19], s[0:1]
	s_waitcnt vmcnt(45)
	v_lshlrev_b32_e32 v12, 16, v96
	v_and_b32_e32 v96, 0xffff0000, v96
	v_lshlrev_b32_e32 v13, 16, v97
	v_and_b32_e32 v97, 0xffff0000, v97
	v_lshlrev_b32_e32 v14, 16, v98
	v_and_b32_e32 v98, 0xffff0000, v98
	v_lshlrev_b32_e32 v15, 16, v99
	v_and_b32_e32 v99, 0xffff0000, v99
	v_fma_f32 v4, v156, v4, v12
	v_fma_f32 v5, v156, v5, v96
	v_fma_f32 v6, v156, v6, v13
	v_fma_f32 v7, v156, v7, v97
	v_fma_f32 v8, v156, v8, v14
	v_fma_f32 v9, v156, v9, v98
	v_fma_f32 v10, v156, v10, v15
	v_fma_f32 v11, v156, v11, v99
	v_cvt_pk_bf16_f32 v172, v4, v5
	v_cvt_pk_bf16_f32 v173, v6, v7
	v_cvt_pk_bf16_f32 v174, v8, v9
	v_cvt_pk_bf16_f32 v175, v10, v11
	v_add_u32_e32 v95, 0x2080000, v0
	global_store_dwordx4 v95, v[172:175], s[0:1]
	s_waitcnt vmcnt(44)
; __device__ __forceinline__ void unpack8(u32x4 r, float* f) { f[0] = bflo(r.x); f[1] = bfhi(r.x); f[2] = bflo(r.y); f[3] = bfhi(r.y); f[4] = bflo(r.z); f[5] = bfhi(r.z); f[6] = bflo(r.w); f[7] = bfhi(r.w); }
; __device__ __forceinline__ u32x4 pack8(const float* f) { u32x4 o; o.x = pk2(f[0], f[1]); o.y = pk2(f[2], f[3]); o.z = pk2(f[4], f[5]); o.w = pk2(f[6], f[7]); return o; }
; __device__ __forceinline__ void phase_scan(const PT& p, int tid) {
;     ...
;         for (int c = 0; c < 16; ++c) {
;             const size_t off = ((size_t)(b * 16 + c) * 32 * 64 * 16 + rem) * 8;
;             *(u32x4*)(PV + off) = pack8(run);
;             if (c < 15) { float s[8]; unpack8(*(const u32x4*)(ST + off), s); const float cd = CD[(b * 16 + c) * 32 + hh];
; #pragma unroll
;                 for (int j = 0; j < 8; ++j) run[j] = run[j] * cd + s[j]; }
	v_lshlrev_b32_e32 v12, 16, v100
	v_and_b32_e32 v100, 0xffff0000, v100
	v_lshlrev_b32_e32 v13, 16, v101
	v_and_b32_e32 v101, 0xffff0000, v101
	v_lshlrev_b32_e32 v14, 16, v102
	v_and_b32_e32 v102, 0xffff0000, v102
	v_lshlrev_b32_e32 v15, 16, v103
	v_and_b32_e32 v103, 0xffff0000, v103
	v_fma_f32 v4, v157, v4, v12
	v_fma_f32 v5, v157, v5, v100
	v_fma_f32 v6, v157, v6, v13
	v_fma_f32 v7, v157, v7, v101
	v_fma_f32 v8, v157, v8, v14
	v_fma_f32 v9, v157, v9, v102
	v_fma_f32 v10, v157, v10, v15
	v_fma_f32 v11, v157, v11, v103
	v_cvt_pk_bf16_f32 v16, v4, v5
	v_cvt_pk_bf16_f32 v17, v6, v7
	v_cvt_pk_bf16_f32 v18, v8, v9
	v_cvt_pk_bf16_f32 v19, v10, v11
	v_add_u32_e32 v3, 0x2100000, v0
	global_store_dwordx4 v3, v[16:19], s[0:1]
	s_waitcnt vmcnt(43)
	v_lshlrev_b32_e32 v12, 16, v104
	v_and_b32_e32 v104, 0xffff0000, v104
	v_lshlrev_b32_e32 v13, 16, v105
	v_and_b32_e32 v105, 0xffff0000, v105
	v_lshlrev_b32_e32 v14, 16, v106
	v_and_b32_e32 v106, 0xffff0000, v106
	v_lshlrev_b32_e32 v15, 16, v107
	v_and_b32_e32 v107, 0xffff0000, v107
	v_fma_f32 v4, v158, v4, v12
	v_fma_f32 v5, v158, v5, v104
	v_fma_f32 v6, v158, v6, v13
	v_fma_f32 v7, v158, v7, v105
	v_fma_f32 v8, v158, v8, v14
	v_fma_f32 v9, v158, v9, v106
	v_fma_f32 v10, v158, v10, v15
	v_fma_f32 v11, v158, v11, v107
	v_cvt_pk_bf16_f32 v172, v4, v5
	v_cvt_pk_bf16_f32 v173, v6, v7
	v_cvt_pk_bf16_f32 v174, v8, v9
	v_cvt_pk_bf16_f32 v175, v10, v11
	v_add_u32_e32 v95, 0x2180000, v0
	global_store_dwordx4 v95, v[172:175], s[0:1]
	s_waitcnt vmcnt(42)
	v_lshlrev_b32_e32 v12, 16, v108
	v_and_b32_e32 v108, 0xffff0000, v108
	v_lshlrev_b32_e32 v13, 16, v109
	v_and_b32_e32 v109, 0xffff0000, v109
	v_lshlrev_b32_e32 v14, 16, v110
	v_and_b32_e32 v110, 0xffff0000, v110
	v_lshlrev_b32_e32 v15, 16, v111
	v_and_b32_e32 v111, 0xffff0000, v111
	v_fma_f32 v4, v159, v4, v12
	v_fma_f32 v5, v159, v5, v108
	v_fma_f32 v6, v159, v6, v13
	v_fma_f32 v7, v159, v7, v109
	v_fma_f32 v8, v159, v8, v14
	v_fma_f32 v9, v159, v9, v110
	v_fma_f32 v10, v159, v10, v15
	v_fma_f32 v11, v159, v11, v111
	v_cvt_pk_bf16_f32 v16, v4, v5
	v_cvt_pk_bf16_f32 v17, v6, v7
	v_cvt_pk_bf16_f32 v18, v8, v9
	v_cvt_pk_bf16_f32 v19, v10, v11
	v_add_u32_e32 v3, 0x2200000, v0
	global_store_dwordx4 v3, v[16:19], s[0:1]
	s_waitcnt vmcnt(41)
	v_lshlrev_b32_e32 v12, 16, v112
	v_and_b32_e32 v112, 0xffff0000, v112
	v_lshlrev_b32_e32 v13, 16, v113
	v_and_b32_e32 v113, 0xffff0000, v113
	v_lshlrev_b32_e32 v14, 16, v114
	v_and_b32_e32 v114, 0xffff0000, v114
	v_lshlrev_b32_e32 v15, 16, v115
	v_and_b32_e32 v115, 0xffff0000, v115
	v_fma_f32 v4, v160, v4, v12
	v_fma_f32 v5, v160, v5, v112
	v_fma_f32 v6, v160, v6, v13
	v_fma_f32 v7, v160, v7, v113
	v_fma_f32 v8, v160, v8, v14
	v_fma_f32 v9, v160, v9, v114
	v_fma_f32 v10, v160, v10, v15
	v_fma_f32 v11, v160, v11, v115
	v_cvt_pk_bf16_f32 v172, v4, v5
	v_cvt_pk_bf16_f32 v173, v6, v7
	v_cvt_pk_bf16_f32 v174, v8, v9
	v_cvt_pk_bf16_f32 v175, v10, v11
	v_add_u32_e32 v95, 0x2280000, v0
	global_store_dwordx4 v95, v[172:175], s[0:1]
	s_waitcnt vmcnt(40)
	v_lshlrev_b32_e32 v12, 16, v116
	v_and_b32_e32 v116, 0xffff0000, v116
	v_lshlrev_b32_e32 v13, 16, v117
	v_and_b32_e32 v117, 0xffff0000, v117
	v_lshlrev_b32_e32 v14, 16, v118
	v_and_b32_e32 v118, 0xffff0000, v118
	v_lshlrev_b32_e32 v15, 16, v119
	v_and_b32_e32 v119, 0xffff0000, v119
	v_fma_f32 v4, v161, v4, v12
	v_fma_f32 v5, v161, v5, v116
	v_fma_f32 v6, v161, v6, v13
	v_fma_f32 v7, v161, v7, v117
	v_fma_f32 v8, v161, v8, v14
	v_fma_f32 v9, v161, v9, v118
	v_fma_f32 v10, v161, v10, v15
	v_fma_f32 v11, v161, v11, v119
	v_cvt_pk_bf16_f32 v16, v4, v5
	v_cvt_pk_bf16_f32 v17, v6, v7
	v_cvt_pk_bf16_f32 v18, v8, v9
	v_cvt_pk_bf16_f32 v19, v10, v11
	v_add_u32_e32 v3, 0x2300000, v0
	global_store_dwordx4 v3, v[16:19], s[0:1]
	s_waitcnt vmcnt(39)
	v_lshlrev_b32_e32 v12, 16, v120
	v_and_b32_e32 v120, 0xffff0000, v120
	v_lshlrev_b32_e32 v13, 16, v121
	v_and_b32_e32 v121, 0xffff0000, v121
	v_lshlrev_b32_e32 v14, 16, v122
	v_and_b32_e32 v122, 0xffff0000, v122
	v_lshlrev_b32_e32 v15, 16, v123
	v_and_b32_e32 v123, 0xffff0000, v123
	v_fma_f32 v4, v162, v4, v12
	v_fma_f32 v5, v162, v5, v120
	v_fma_f32 v6, v162, v6, v13
	v_fma_f32 v7, v162, v7, v121
	v_fma_f32 v8, v162, v8, v14
	v_fma_f32 v9, v162, v9, v122
	v_fma_f32 v10, v162, v10, v15
	v_fma_f32 v11, v162, v11, v123
	v_cvt_pk_bf16_f32 v172, v4, v5
	v_cvt_pk_bf16_f32 v173, v6, v7
	v_cvt_pk_bf16_f32 v174, v8, v9
	v_cvt_pk_bf16_f32 v175, v10, v11
	v_add_u32_e32 v95, 0x2380000, v0
	global_store_dwordx4 v95, v[172:175], s[0:1]
	s_waitcnt vmcnt(38)
	v_lshlrev_b32_e32 v12, 16, v124
	v_and_b32_e32 v124, 0xffff0000, v124
	v_lshlrev_b32_e32 v13, 16, v125
	v_and_b32_e32 v125, 0xffff0000, v125
	v_lshlrev_b32_e32 v14, 16, v126
	v_and_b32_e32 v126, 0xffff0000, v126
	v_lshlrev_b32_e32 v15, 16, v127
	v_and_b32_e32 v127, 0xffff0000, v127
	v_fma_f32 v4, v163, v4, v12
	v_fma_f32 v5, v163, v5, v124
	v_fma_f32 v6, v163, v6, v13
	v_fma_f32 v7, v163, v7, v125
	v_fma_f32 v8, v163, v8, v14
	v_fma_f32 v9, v163, v9, v126
	v_fma_f32 v10, v163, v10, v15
	v_fma_f32 v11, v163, v11, v127
	v_cvt_pk_bf16_f32 v16, v4, v5
	v_cvt_pk_bf16_f32 v17, v6, v7
	v_cvt_pk_bf16_f32 v18, v8, v9
	v_cvt_pk_bf16_f32 v19, v10, v11
	v_add_u32_e32 v3, 0x2400000, v0
	global_store_dwordx4 v3, v[16:19], s[0:1]
	s_waitcnt vmcnt(37)
; __device__ __forceinline__ void unpack8(u32x4 r, float* f) { f[0] = bflo(r.x); f[1] = bfhi(r.x); f[2] = bflo(r.y); f[3] = bfhi(r.y); f[4] = bflo(r.z); f[5] = bfhi(r.z); f[6] = bflo(r.w); f[7] = bfhi(r.w); }
; __device__ __forceinline__ u32x4 pack8(const float* f) { u32x4 o; o.x = pk2(f[0], f[1]); o.y = pk2(f[2], f[3]); o.z = pk2(f[4], f[5]); o.w = pk2(f[6], f[7]); return o; }
; __device__ __forceinline__ void phase_scan(const PT& p, int tid) {
;     ...
;         for (int c = 0; c < 16; ++c) {
;             const size_t off = ((size_t)(b * 16 + c) * 32 * 64 * 16 + rem) * 8;
;             *(u32x4*)(PV + off) = pack8(run);
;             if (c < 15) { float s[8]; unpack8(*(const u32x4*)(ST + off), s); const float cd = CD[(b * 16 + c) * 32 + hh];
; #pragma unroll
;                 for (int j = 0; j < 8; ++j) run[j] = run[j] * cd + s[j]; }
	v_lshlrev_b32_e32 v12, 16, v128
	v_and_b32_e32 v128, 0xffff0000, v128
	v_lshlrev_b32_e32 v13, 16, v129
	v_and_b32_e32 v129, 0xffff0000, v129
	v_lshlrev_b32_e32 v14, 16, v130
	v_and_b32_e32 v130, 0xffff0000, v130
	v_lshlrev_b32_e32 v15, 16, v131
	v_and_b32_e32 v131, 0xffff0000, v131
	v_fma_f32 v4, v164, v4, v12
	v_fma_f32 v5, v164, v5, v128
	v_fma_f32 v6, v164, v6, v13
	v_fma_f32 v7, v164, v7, v129
	v_fma_f32 v8, v164, v8, v14
	v_fma_f32 v9, v164, v9, v130
	v_fma_f32 v10, v164, v10, v15
	v_fma_f32 v11, v164, v11, v131
	v_cvt_pk_bf16_f32 v172, v4, v5
	v_cvt_pk_bf16_f32 v173, v6, v7
	v_cvt_pk_bf16_f32 v174, v8, v9
	v_cvt_pk_bf16_f32 v175, v10, v11
	v_add_u32_e32 v95, 0x2480000, v0
	global_store_dwordx4 v95, v[172:175], s[0:1]
	s_waitcnt vmcnt(36)
	v_lshlrev_b32_e32 v12, 16, v132
	v_and_b32_e32 v132, 0xffff0000, v132
	v_lshlrev_b32_e32 v13, 16, v133
	v_and_b32_e32 v133, 0xffff0000, v133
	v_lshlrev_b32_e32 v14, 16, v134
	v_and_b32_e32 v134, 0xffff0000, v134
	v_lshlrev_b32_e32 v15, 16, v135
	v_and_b32_e32 v135, 0xffff0000, v135
	v_fma_f32 v4, v165, v4, v12
	v_fma_f32 v5, v165, v5, v132
	v_fma_f32 v6, v165, v6, v13
	v_fma_f32 v7, v165, v7, v133
	v_fma_f32 v8, v165, v8, v14
	v_fma_f32 v9, v165, v9, v134
	v_fma_f32 v10, v165, v10, v15
	v_fma_f32 v11, v165, v11, v135
	v_cvt_pk_bf16_f32 v16, v4, v5
	v_cvt_pk_bf16_f32 v17, v6, v7
	v_cvt_pk_bf16_f32 v18, v8, v9
	v_cvt_pk_bf16_f32 v19, v10, v11
	v_add_u32_e32 v3, 0x2500000, v0
	global_store_dwordx4 v3, v[16:19], s[0:1]
	s_waitcnt vmcnt(35)
	v_lshlrev_b32_e32 v12, 16, v136
	v_and_b32_e32 v136, 0xffff0000, v136
	v_lshlrev_b32_e32 v13, 16, v137
	v_and_b32_e32 v137, 0xffff0000, v137
	v_lshlrev_b32_e32 v14, 16, v138
	v_and_b32_e32 v138, 0xffff0000, v138
	v_lshlrev_b32_e32 v15, 16, v139
	v_and_b32_e32 v139, 0xffff0000, v139
	v_fma_f32 v4, v166, v4, v12
	v_fma_f32 v5, v166, v5, v136
	v_fma_f32 v6, v166, v6, v13
	v_fma_f32 v7, v166, v7, v137
	v_fma_f32 v8, v166, v8, v14
	v_fma_f32 v9, v166, v9, v138
	v_fma_f32 v10, v166, v10, v15
	v_fma_f32 v11, v166, v11, v139
	v_cvt_pk_bf16_f32 v172, v4, v5
	v_cvt_pk_bf16_f32 v173, v6, v7
	v_cvt_pk_bf16_f32 v174, v8, v9
	v_cvt_pk_bf16_f32 v175, v10, v11
	v_add_u32_e32 v95, 0x2580000, v0
	global_store_dwordx4 v95, v[172:175], s[0:1]
	s_waitcnt vmcnt(34)
	v_lshlrev_b32_e32 v12, 16, v140
	v_and_b32_e32 v140, 0xffff0000, v140
	v_lshlrev_b32_e32 v13, 16, v141
	v_and_b32_e32 v141, 0xffff0000, v141
	v_lshlrev_b32_e32 v14, 16, v142
	v_and_b32_e32 v142, 0xffff0000, v142
	v_lshlrev_b32_e32 v15, 16, v143
	v_and_b32_e32 v143, 0xffff0000, v143
	v_fma_f32 v4, v167, v4, v12
	v_fma_f32 v5, v167, v5, v140
	v_fma_f32 v6, v167, v6, v13
	v_fma_f32 v7, v167, v7, v141
	v_fma_f32 v8, v167, v8, v14
	v_fma_f32 v9, v167, v9, v142
	v_fma_f32 v10, v167, v10, v15
	v_fma_f32 v11, v167, v11, v143
	v_cvt_pk_bf16_f32 v16, v4, v5
	v_cvt_pk_bf16_f32 v17, v6, v7
	v_cvt_pk_bf16_f32 v18, v8, v9
	v_cvt_pk_bf16_f32 v19, v10, v11
	v_add_u32_e32 v3, 0x2600000, v0
	global_store_dwordx4 v3, v[16:19], s[0:1]
	s_waitcnt vmcnt(33)
	v_lshlrev_b32_e32 v12, 16, v144
	v_and_b32_e32 v144, 0xffff0000, v144
	v_lshlrev_b32_e32 v13, 16, v145
	v_and_b32_e32 v145, 0xffff0000, v145
	v_lshlrev_b32_e32 v14, 16, v146
	v_and_b32_e32 v146, 0xffff0000, v146
	v_lshlrev_b32_e32 v15, 16, v147
	v_and_b32_e32 v147, 0xffff0000, v147
	v_fma_f32 v4, v168, v4, v12
	v_fma_f32 v5, v168, v5, v144
	v_fma_f32 v6, v168, v6, v13
	v_fma_f32 v7, v168, v7, v145
	v_fma_f32 v8, v168, v8, v14
	v_fma_f32 v9, v168, v9, v146
	v_fma_f32 v10, v168, v10, v15
	v_fma_f32 v11, v168, v11, v147
	v_cvt_pk_bf16_f32 v172, v4, v5
	v_cvt_pk_bf16_f32 v173, v6, v7
	v_cvt_pk_bf16_f32 v174, v8, v9
	v_cvt_pk_bf16_f32 v175, v10, v11
	v_add_u32_e32 v95, 0x2680000, v0
	global_store_dwordx4 v95, v[172:175], s[0:1]
	s_waitcnt vmcnt(32)
	v_lshlrev_b32_e32 v12, 16, v148
	v_and_b32_e32 v148, 0xffff0000, v148
	v_lshlrev_b32_e32 v13, 16, v149
	v_and_b32_e32 v149, 0xffff0000, v149
	v_lshlrev_b32_e32 v14, 16, v150
	v_and_b32_e32 v150, 0xffff0000, v150
	v_lshlrev_b32_e32 v15, 16, v151
	v_and_b32_e32 v151, 0xffff0000, v151
	v_fma_f32 v4, v169, v4, v12
	v_fma_f32 v5, v169, v5, v148
	v_fma_f32 v6, v169, v6, v13
	v_fma_f32 v7, v169, v7, v149
	v_fma_f32 v8, v169, v8, v14
	v_fma_f32 v9, v169, v9, v150
	v_fma_f32 v10, v169, v10, v15
	v_fma_f32 v11, v169, v11, v151
	v_cvt_pk_bf16_f32 v16, v4, v5
	v_cvt_pk_bf16_f32 v17, v6, v7
	v_cvt_pk_bf16_f32 v18, v8, v9
	v_cvt_pk_bf16_f32 v19, v10, v11
	v_add_u32_e32 v3, 0x2700000, v0
	global_store_dwordx4 v3, v[16:19], s[0:1]
	s_waitcnt vmcnt(31)
	v_lshlrev_b32_e32 v12, 16, v152
	v_and_b32_e32 v152, 0xffff0000, v152
	v_lshlrev_b32_e32 v13, 16, v153
	v_and_b32_e32 v153, 0xffff0000, v153
	v_lshlrev_b32_e32 v14, 16, v154
	v_and_b32_e32 v154, 0xffff0000, v154
	v_lshlrev_b32_e32 v15, 16, v155
	v_and_b32_e32 v155, 0xffff0000, v155
	v_fma_f32 v4, v170, v4, v12
	v_fma_f32 v5, v170, v5, v152
	v_fma_f32 v6, v170, v6, v13
	v_fma_f32 v7, v170, v7, v153
	v_fma_f32 v8, v170, v8, v14
	v_fma_f32 v9, v170, v9, v154
	v_fma_f32 v10, v170, v10, v15
	v_fma_f32 v11, v170, v11, v155
	v_cvt_pk_bf16_f32 v172, v4, v5
	v_cvt_pk_bf16_f32 v173, v6, v7
	v_cvt_pk_bf16_f32 v174, v8, v9
	v_cvt_pk_bf16_f32 v175, v10, v11
	v_add_u32_e32 v95, 0x2780000, v0
	global_store_dwordx4 v95, v[172:175], s[0:1]

; __device__ __forceinline__ void unpack8(u32x4 r, float* f) { f[0] = bflo(r.x); f[1] = bfhi(r.x); f[2] = bflo(r.y); f[3] = bfhi(r.y); f[4] = bflo(r.z); f[5] = bfhi(r.z); f[6] = bflo(r.w); f[7] = bfhi(r.w); }
;     __device__ __forceinline__ PT() { out = (float*)(__attribute__((address_space(1))) float*)ptab_get(23); ws = (unsigned char*)(__attribute__((address_space(1))) unsigned char*)ptab_get(24); }
; __device__ __forceinline__ void phase_final(const PT& p, int lane, int wave) {
;     const float* st2 = (const float*)(p.ws + WS_ST2); const float* g = p.in[22]; const bf16* X2 = (const bf16*)(p.ws + WS_X2B);
;     for (int m = blockIdx.x * 8 + wave; m < M; m += gridDim.x * 8) {
;         const float rs = rsqrtf(st2[m] * (1.f / 2048.f) + EPS);
;         const u32x4* xr = (const u32x4*)(X2 + (size_t)m * 2048) + lane; f32x4* orow = (f32x4*)(p.out + (size_t)m * 2048);
; #pragma unroll
;         for (int j = 0; j < 4; ++j) {
;             float f[8]; unpack8(xr[64 * j], f); const int c = 8 * (lane + 64 * j);
.LBB0_1257:
	s_or_b64 exec, exec, s[0:1]
	s_waitcnt lgkmcnt(0)
	v_mov_b32_e32 v0, 0x23eb8
	s_barrier
	ds_read_b64 v[0:1], v0
	v_mov_b32_e32 v2, 0x23ec0
	ds_read_b64 v[2:3], v2
	v_readlane_b32 s1, v249, 2
	s_waitcnt lgkmcnt(1)
	v_readfirstlane_b32 s7, v0
	v_mov_b32_e32 v0, 0x23eb0
	v_readfirstlane_b32 s6, v1
	ds_read_b64 v[0:1], v0
	v_readfirstlane_b32 s0, v196
	s_ashr_i32 s0, s0, 6
	s_add_i32 s0, s0, s1
	s_waitcnt lgkmcnt(1)
	v_readfirstlane_b32 s5, v3
	v_readfirstlane_b32 s4, v2
	s_waitcnt lgkmcnt(0)
	v_readfirstlane_b32 s3, v1
	s_cmpk_gt_i32 s0, 0x3fff
	v_readfirstlane_b32 s2, v0
	s_cbranch_scc1 .LBB0_1260
	v_and_b32_e32 v10, 63, v196
	v_lshlrev_b32_e32 v0, 4, v10
	v_mov_b32_e32 v1, 0
	v_lshl_add_u64 v[2:3], s[4:5], 0, v[0:1]
	v_lshlrev_b32_e32 v0, 5, v10
	v_or_b32_e32 v8, 64, v10
	v_lshl_add_u64 v[4:5], s[2:3], 0, v[0:1]
	v_lshlrev_b32_e32 v0, 5, v8
	v_or_b32_e32 v11, 0x80, v10
	s_add_u32 s8, s4, 0x30000
	v_lshl_add_u64 v[6:7], s[2:3], 0, v[0:1]
	v_lshlrev_b32_e32 v0, 5, v11
	v_or_b32_e32 v13, 0xc0, v10
	s_addc_u32 s9, s5, 0
	s_mov_b64 s[4:5], 0x6900000
	v_lshlrev_b32_e32 v12, 1, v10
	v_lshlrev_b32_e32 v14, 1, v8
	v_lshl_add_u64 v[8:9], s[2:3], 0, v[0:1]
	v_lshlrev_b32_e32 v16, 1, v11
	v_lshlrev_b32_e32 v0, 5, v13
	v_lshlrev_b32_e32 v18, 1, v13
	v_lshl_add_u64 v[2:3], v[2:3], 0, s[4:5]
	v_lshl_add_u64 v[10:11], s[2:3], 0, v[0:1]
	v_mov_b32_e32 v0, 0x3727c5ac
	s_mov_b32 s4, 0x800000
	v_lshlrev_b32_e32 v12, 4, v12
	v_lshlrev_b32_e32 v13, 4, v14
	v_lshlrev_b32_e32 v14, 4, v16
	v_lshlrev_b32_e32 v15, 4, v18
	s_mov_b32 s14, s0
	global_load_dwordx4 v[16:19], v[4:5], off
	global_load_dwordx4 v[20:23], v[4:5], off offset:16
	global_load_dwordx4 v[24:27], v[6:7], off
	global_load_dwordx4 v[28:31], v[6:7], off offset:16
	global_load_dwordx4 v[32:35], v[8:9], off
	global_load_dwordx4 v[36:39], v[8:9], off offset:16
	global_load_dwordx4 v[40:43], v[10:11], off
	global_load_dwordx4 v[44:47], v[10:11], off offset:16
	s_ashr_i32 s1, s0, 31
	s_lshl_b64 s[12:13], s[0:1], 2
	s_add_u32 s12, s8, s12
	s_addc_u32 s13, s9, s13
	global_load_dword v48, v1, s[12:13]
	s_lshl_b64 s[12:13], s[0:1], 12
	v_lshl_add_u64 v[216:217], v[2:3], 0, s[12:13]
	global_load_dwordx4 v[64:67], v[216:217], off nt
	global_load_dwordx4 v[68:71], v[216:217], off offset:1024 nt
	global_load_dwordx4 v[72:75], v[216:217], off offset:2048 nt
	global_load_dwordx4 v[76:79], v[216:217], off offset:3072 nt
	s_add_i32 s0, s0, s80
	s_ashr_i32 s1, s0, 31
	s_lshl_b64 s[12:13], s[0:1], 2
	s_add_u32 s12, s8, s12
	s_addc_u32 s13, s9, s13
	global_load_dword v49, v1, s[12:13]
	s_lshl_b64 s[12:13], s[0:1], 12
	v_lshl_add_u64 v[220:221], v[2:3], 0, s[12:13]
	global_load_dwordx4 v[80:83], v[220:221], off nt
	global_load_dwordx4 v[84:87], v[220:221], off offset:1024 nt
	global_load_dwordx4 v[88:91], v[220:221], off offset:2048 nt
	global_load_dwordx4 v[92:95], v[220:221], off offset:3072 nt
	s_add_i32 s0, s0, s80
	s_ashr_i32 s1, s0, 31
	s_lshl_b64 s[12:13], s[0:1], 2
	s_add_u32 s12, s8, s12
	s_addc_u32 s13, s9, s13
	global_load_dword v50, v1, s[12:13]
	s_lshl_b64 s[12:13], s[0:1], 12
	v_lshl_add_u64 v[216:217], v[2:3], 0, s[12:13]
	global_load_dwordx4 v[96:99], v[216:217], off nt
	global_load_dwordx4 v[100:103], v[216:217], off offset:1024 nt
	global_load_dwordx4 v[104:107], v[216:217], off offset:2048 nt
	global_load_dwordx4 v[108:111], v[216:217], off offset:3072 nt
	s_add_i32 s0, s0, s80
	s_ashr_i32 s1, s0, 31
	s_lshl_b64 s[12:13], s[0:1], 2
	s_add_u32 s12, s8, s12
	s_addc_u32 s13, s9, s13
	global_load_dword v51, v1, s[12:13]
	s_lshl_b64 s[12:13], s[0:1], 12
	v_lshl_add_u64 v[220:221], v[2:3], 0, s[12:13]
	global_load_dwordx4 v[112:115], v[220:221], off nt
	global_load_dwordx4 v[116:119], v[220:221], off offset:1024 nt
	global_load_dwordx4 v[120:123], v[220:221], off offset:2048 nt
	global_load_dwordx4 v[124:127], v[220:221], off offset:3072 nt
	s_add_i32 s0, s0, s80
	s_ashr_i32 s1, s0, 31
	s_lshl_b64 s[12:13], s[0:1], 2
	s_add_u32 s12, s8, s12
	s_addc_u32 s13, s9, s13
	global_load_dword v52, v1, s[12:13]
	s_lshl_b64 s[12:13], s[0:1], 12
	v_lshl_add_u64 v[216:217], v[2:3], 0, s[12:13]
	global_load_dwordx4 v[128:131], v[216:217], off nt
	global_load_dwordx4 v[132:135], v[216:217], off offset:1024 nt
	global_load_dwordx4 v[136:139], v[216:217], off offset:2048 nt
	global_load_dwordx4 v[140:143], v[216:217], off offset:3072 nt
	s_add_i32 s0, s0, s80
	s_ashr_i32 s1, s0, 31
	s_lshl_b64 s[12:13], s[0:1], 2
	s_add_u32 s12, s8, s12
	s_addc_u32 s13, s9, s13
	global_load_dword v53, v1, s[12:13]
	s_lshl_b64 s[12:13], s[0:1], 12
	v_lshl_add_u64 v[220:221], v[2:3], 0, s[12:13]
	global_load_dwordx4 v[144:147], v[220:221], off nt
	global_load_dwordx4 v[148:151], v[220:221], off offset:1024 nt
	global_load_dwordx4 v[152:155], v[220:221], off offset:2048 nt
	global_load_dwordx4 v[156:159], v[220:221], off offset:3072 nt
	s_add_i32 s0, s0, s80
	s_ashr_i32 s1, s0, 31
	s_lshl_b64 s[12:13], s[0:1], 2
	s_add_u32 s12, s8, s12
	s_addc_u32 s13, s9, s13
	global_load_dword v54, v1, s[12:13]
	s_lshl_b64 s[12:13], s[0:1], 12
	v_lshl_add_u64 v[216:217], v[2:3], 0, s[12:13]
	global_load_dwordx4 v[160:163], v[216:217], off nt
	global_load_dwordx4 v[164:167], v[216:217], off offset:1024 nt
	global_load_dwordx4 v[168:171], v[216:217], off offset:2048 nt
	global_load_dwordx4 v[172:175], v[216:217], off offset:3072 nt
	s_add_i32 s0, s0, s80
	s_ashr_i32 s1, s0, 31
	s_lshl_b64 s[12:13], s[0:1], 2
	s_add_u32 s12, s8, s12
	s_addc_u32 s13, s9, s13
	global_load_dword v55, v1, s[12:13]
	s_lshl_b64 s[12:13], s[0:1], 12
	v_lshl_add_u64 v[220:221], v[2:3], 0, s[12:13]
	global_load_dwordx4 v[176:179], v[220:221], off nt
	global_load_dwordx4 v[180:183], v[220:221], off offset:1024 nt
	global_load_dwordx4 v[184:187], v[220:221], off offset:2048 nt
	global_load_dwordx4 v[188:191], v[220:221], off offset:3072 nt
	s_add_i32 s0, s0, s80
	s_mov_b32 s0, s14
	s_ashr_i32 s1, s0, 31
	s_lshl_b64 s[2:3], s[0:1], 13
	s_add_u32 s2, s7, s2
	s_addc_u32 s3, s6, s3
	s_add_i32 s0, s0, s80
	s_waitcnt vmcnt(39)
; __device__ __forceinline__ void unpack8(u32x4 r, float* f) { f[0] = bflo(r.x); f[1] = bfhi(r.x); f[2] = bflo(r.y); f[3] = bfhi(r.y); f[4] = bflo(r.z); f[5] = bfhi(r.z); f[6] = bflo(r.w); f[7] = bfhi(r.w); }
; __device__ __forceinline__ void phase_final(const PT& p, int lane, int wave) {
;     ...
;         const float rs = rsqrtf(st2[m] * (1.f / 2048.f) + EPS);
;         const u32x4* xr = (const u32x4*)(X2 + (size_t)m * 2048) + lane; f32x4* orow = (f32x4*)(p.out + (size_t)m * 2048);
; #pragma unroll
;         for (int j = 0; j < 4; ++j) {
;             float f[8]; unpack8(xr[64 * j], f); const int c = 8 * (lane + 64 * j);
;             const f32x4 g0 = *(const f32x4*)(g + c), g1 = *(const f32x4*)(g + c + 4);
;             orow[(c >> 2)] = (f32x4){f[0] * rs * g0.x, f[1] * rs * g0.y, f[2] * rs * g0.z, f[3] * rs * g0.w};
;             orow[(c >> 2) + 1] = (f32x4){f[4] * rs * g1.x, f[5] * rs * g1.y, f[6] * rs * g1.z, f[7] * rs * g1.w};
	v_fmamk_f32 v220, v48, 0x3a000000, v0
	v_mul_f32_e32 v221, 0x4b800000, v220
	v_cmp_gt_f32_e32 vcc, s4, v220
	s_nop 1
	v_cndmask_b32_e32 v220, v220, v221, vcc
	v_rsq_f32_e32 v218, v220
	s_nop 0
	v_mul_f32_e32 v221, 0x45800000, v218
	v_cndmask_b32_e32 v218, v218, v221, vcc
	s_waitcnt vmcnt(38)
	v_lshlrev_b32_e32 v200, 16, v64
	v_and_b32_e32 v201, 0xffff0000, v64
	v_lshlrev_b32_e32 v202, 16, v65
	v_and_b32_e32 v203, 0xffff0000, v65
	v_lshlrev_b32_e32 v204, 16, v66
	v_and_b32_e32 v205, 0xffff0000, v66
	v_lshlrev_b32_e32 v206, 16, v67
	v_and_b32_e32 v207, 0xffff0000, v67
	v_pk_mul_f32 v[200:201], v[218:219], v[200:201] op_sel_hi:[0,1]
	v_pk_mul_f32 v[202:203], v[218:219], v[202:203] op_sel_hi:[0,1]
	v_pk_mul_f32 v[204:205], v[218:219], v[204:205] op_sel_hi:[0,1]
	v_pk_mul_f32 v[206:207], v[218:219], v[206:207] op_sel_hi:[0,1]
	v_pk_mul_f32 v[208:209], v[16:17], v[200:201]
	v_pk_mul_f32 v[210:211], v[18:19], v[202:203]
	v_pk_mul_f32 v[212:213], v[20:21], v[204:205]
	v_pk_mul_f32 v[214:215], v[22:23], v[206:207]
	global_store_dwordx4 v12, v[208:211], s[2:3]
	global_store_dwordx4 v12, v[212:215], s[2:3] offset:16
	s_waitcnt vmcnt(39)
	v_lshlrev_b32_e32 v200, 16, v68
	v_and_b32_e32 v201, 0xffff0000, v68
	v_lshlrev_b32_e32 v202, 16, v69
	v_and_b32_e32 v203, 0xffff0000, v69
	v_lshlrev_b32_e32 v204, 16, v70
	v_and_b32_e32 v205, 0xffff0000, v70
	v_lshlrev_b32_e32 v206, 16, v71
	v_and_b32_e32 v207, 0xffff0000, v71
	v_pk_mul_f32 v[200:201], v[218:219], v[200:201] op_sel_hi:[0,1]
	v_pk_mul_f32 v[202:203], v[218:219], v[202:203] op_sel_hi:[0,1]
	v_pk_mul_f32 v[204:205], v[218:219], v[204:205] op_sel_hi:[0,1]
	v_pk_mul_f32 v[206:207], v[218:219], v[206:207] op_sel_hi:[0,1]
	v_pk_mul_f32 v[224:225], v[24:25], v[200:201]
	v_pk_mul_f32 v[226:227], v[26:27], v[202:203]
	v_pk_mul_f32 v[228:229], v[28:29], v[204:205]
	v_pk_mul_f32 v[230:231], v[30:31], v[206:207]
	global_store_dwordx4 v13, v[224:227], s[2:3]
	global_store_dwordx4 v13, v[228:231], s[2:3] offset:16
	s_waitcnt vmcnt(40)
	v_lshlrev_b32_e32 v200, 16, v72
	v_and_b32_e32 v201, 0xffff0000, v72
	v_lshlrev_b32_e32 v202, 16, v73
	v_and_b32_e32 v203, 0xffff0000, v73
	v_lshlrev_b32_e32 v204, 16, v74
	v_and_b32_e32 v205, 0xffff0000, v74
	v_lshlrev_b32_e32 v206, 16, v75
	v_and_b32_e32 v207, 0xffff0000, v75
	v_pk_mul_f32 v[200:201], v[218:219], v[200:201] op_sel_hi:[0,1]
	v_pk_mul_f32 v[202:203], v[218:219], v[202:203] op_sel_hi:[0,1]
	v_pk_mul_f32 v[204:205], v[218:219], v[204:205] op_sel_hi:[0,1]
	v_pk_mul_f32 v[206:207], v[218:219], v[206:207] op_sel_hi:[0,1]
	v_pk_mul_f32 v[208:209], v[32:33], v[200:201]
	v_pk_mul_f32 v[210:211], v[34:35], v[202:203]
	v_pk_mul_f32 v[212:213], v[36:37], v[204:205]
	v_pk_mul_f32 v[214:215], v[38:39], v[206:207]
	global_store_dwordx4 v14, v[208:211], s[2:3]
	global_store_dwordx4 v14, v[212:215], s[2:3] offset:16
	s_waitcnt vmcnt(41)
	v_lshlrev_b32_e32 v200, 16, v76
	v_and_b32_e32 v201, 0xffff0000, v76
	v_lshlrev_b32_e32 v202, 16, v77
	v_and_b32_e32 v203, 0xffff0000, v77
	v_lshlrev_b32_e32 v204, 16, v78
	v_and_b32_e32 v205, 0xffff0000, v78
	v_lshlrev_b32_e32 v206, 16, v79
	v_and_b32_e32 v207, 0xffff0000, v79
	v_pk_mul_f32 v[200:201], v[218:219], v[200:201] op_sel_hi:[0,1]
	v_pk_mul_f32 v[202:203], v[218:219], v[202:203] op_sel_hi:[0,1]
	v_pk_mul_f32 v[204:205], v[218:219], v[204:205] op_sel_hi:[0,1]
	v_pk_mul_f32 v[206:207], v[218:219], v[206:207] op_sel_hi:[0,1]
	v_pk_mul_f32 v[224:225], v[40:41], v[200:201]
	v_pk_mul_f32 v[226:227], v[42:43], v[202:203]
	v_pk_mul_f32 v[228:229], v[44:45], v[204:205]
	v_pk_mul_f32 v[230:231], v[46:47], v[206:207]
	global_store_dwordx4 v15, v[224:227], s[2:3]
	global_store_dwordx4 v15, v[228:231], s[2:3] offset:16
	s_ashr_i32 s1, s0, 31
	s_lshl_b64 s[2:3], s[0:1], 13
	s_add_u32 s2, s7, s2
	s_addc_u32 s3, s6, s3
	s_add_i32 s0, s0, s80
	s_waitcnt vmcnt(42)
	v_fmamk_f32 v220, v49, 0x3a000000, v0
	v_mul_f32_e32 v221, 0x4b800000, v220
	v_cmp_gt_f32_e32 vcc, s4, v220
	s_nop 1
	v_cndmask_b32_e32 v220, v220, v221, vcc
	v_rsq_f32_e32 v218, v220
	s_nop 0
	v_mul_f32_e32 v221, 0x45800000, v218
	v_cndmask_b32_e32 v218, v218, v221, vcc
	s_waitcnt vmcnt(41)
	v_lshlrev_b32_e32 v200, 16, v80
	v_and_b32_e32 v201, 0xffff0000, v80
	v_lshlrev_b32_e32 v202, 16, v81
	v_and_b32_e32 v203, 0xffff0000, v81
	v_lshlrev_b32_e32 v204, 16, v82
	v_and_b32_e32 v205, 0xffff0000, v82
	v_lshlrev_b32_e32 v206, 16, v83
	v_and_b32_e32 v207, 0xffff0000, v83
	v_pk_mul_f32 v[200:201], v[218:219], v[200:201] op_sel_hi:[0,1]
	v_pk_mul_f32 v[202:203], v[218:219], v[202:203] op_sel_hi:[0,1]
	v_pk_mul_f32 v[204:205], v[218:219], v[204:205] op_sel_hi:[0,1]
	v_pk_mul_f32 v[206:207], v[218:219], v[206:207] op_sel_hi:[0,1]
	v_pk_mul_f32 v[208:209], v[16:17], v[200:201]
	v_pk_mul_f32 v[210:211], v[18:19], v[202:203]
	v_pk_mul_f32 v[212:213], v[20:21], v[204:205]
	v_pk_mul_f32 v[214:215], v[22:23], v[206:207]
	global_store_dwordx4 v12, v[208:211], s[2:3]
	global_store_dwordx4 v12, v[212:215], s[2:3] offset:16
	s_waitcnt vmcnt(42)
	v_lshlrev_b32_e32 v200, 16, v84
	v_and_b32_e32 v201, 0xffff0000, v84
	v_lshlrev_b32_e32 v202, 16, v85
	v_and_b32_e32 v203, 0xffff0000, v85
	v_lshlrev_b32_e32 v204, 16, v86
	v_and_b32_e32 v205, 0xffff0000, v86
	v_lshlrev_b32_e32 v206, 16, v87
	v_and_b32_e32 v207, 0xffff0000, v87
	v_pk_mul_f32 v[200:201], v[218:219], v[200:201] op_sel_hi:[0,1]
	v_pk_mul_f32 v[202:203], v[218:219], v[202:203] op_sel_hi:[0,1]
	v_pk_mul_f32 v[204:205], v[218:219], v[204:205] op_sel_hi:[0,1]
	v_pk_mul_f32 v[206:207], v[218:219], v[206:207] op_sel_hi:[0,1]
	v_pk_mul_f32 v[224:225], v[24:25], v[200:201]
	v_pk_mul_f32 v[226:227], v[26:27], v[202:203]
	v_pk_mul_f32 v[228:229], v[28:29], v[204:205]
	v_pk_mul_f32 v[230:231], v[30:31], v[206:207]
	global_store_dwordx4 v13, v[224:227], s[2:3]
	global_store_dwordx4 v13, v[228:231], s[2:3] offset:16
	s_waitcnt vmcnt(43)
; __device__ __forceinline__ void unpack8(u32x4 r, float* f) { f[0] = bflo(r.x); f[1] = bfhi(r.x); f[2] = bflo(r.y); f[3] = bfhi(r.y); f[4] = bflo(r.z); f[5] = bfhi(r.z); f[6] = bflo(r.w); f[7] = bfhi(r.w); }
; __device__ __forceinline__ void phase_final(const PT& p, int lane, int wave) {
;     ...
;         const float rs = rsqrtf(st2[m] * (1.f / 2048.f) + EPS);
;         const u32x4* xr = (const u32x4*)(X2 + (size_t)m * 2048) + lane; f32x4* orow = (f32x4*)(p.out + (size_t)m * 2048);
; #pragma unroll
;         for (int j = 0; j < 4; ++j) {
;             float f[8]; unpack8(xr[64 * j], f); const int c = 8 * (lane + 64 * j);
;             const f32x4 g0 = *(const f32x4*)(g + c), g1 = *(const f32x4*)(g + c + 4);
;             orow[(c >> 2)] = (f32x4){f[0] * rs * g0.x, f[1] * rs * g0.y, f[2] * rs * g0.z, f[3] * rs * g0.w};
;             orow[(c >> 2) + 1] = (f32x4){f[4] * rs * g1.x, f[5] * rs * g1.y, f[6] * rs * g1.z, f[7] * rs * g1.w};
	v_lshlrev_b32_e32 v200, 16, v88
	v_and_b32_e32 v201, 0xffff0000, v88
	v_lshlrev_b32_e32 v202, 16, v89
	v_and_b32_e32 v203, 0xffff0000, v89
	v_lshlrev_b32_e32 v204, 16, v90
	v_and_b32_e32 v205, 0xffff0000, v90
	v_lshlrev_b32_e32 v206, 16, v91
	v_and_b32_e32 v207, 0xffff0000, v91
	v_pk_mul_f32 v[200:201], v[218:219], v[200:201] op_sel_hi:[0,1]
	v_pk_mul_f32 v[202:203], v[218:219], v[202:203] op_sel_hi:[0,1]
	v_pk_mul_f32 v[204:205], v[218:219], v[204:205] op_sel_hi:[0,1]
	v_pk_mul_f32 v[206:207], v[218:219], v[206:207] op_sel_hi:[0,1]
	v_pk_mul_f32 v[208:209], v[32:33], v[200:201]
	v_pk_mul_f32 v[210:211], v[34:35], v[202:203]
	v_pk_mul_f32 v[212:213], v[36:37], v[204:205]
	v_pk_mul_f32 v[214:215], v[38:39], v[206:207]
	global_store_dwordx4 v14, v[208:211], s[2:3]
	global_store_dwordx4 v14, v[212:215], s[2:3] offset:16
	s_waitcnt vmcnt(44)
	v_lshlrev_b32_e32 v200, 16, v92
	v_and_b32_e32 v201, 0xffff0000, v92
	v_lshlrev_b32_e32 v202, 16, v93
	v_and_b32_e32 v203, 0xffff0000, v93
	v_lshlrev_b32_e32 v204, 16, v94
	v_and_b32_e32 v205, 0xffff0000, v94
	v_lshlrev_b32_e32 v206, 16, v95
	v_and_b32_e32 v207, 0xffff0000, v95
	v_pk_mul_f32 v[200:201], v[218:219], v[200:201] op_sel_hi:[0,1]
	v_pk_mul_f32 v[202:203], v[218:219], v[202:203] op_sel_hi:[0,1]
	v_pk_mul_f32 v[204:205], v[218:219], v[204:205] op_sel_hi:[0,1]
	v_pk_mul_f32 v[206:207], v[218:219], v[206:207] op_sel_hi:[0,1]
	v_pk_mul_f32 v[224:225], v[40:41], v[200:201]
	v_pk_mul_f32 v[226:227], v[42:43], v[202:203]
	v_pk_mul_f32 v[228:229], v[44:45], v[204:205]
	v_pk_mul_f32 v[230:231], v[46:47], v[206:207]
	global_store_dwordx4 v15, v[224:227], s[2:3]
	global_store_dwordx4 v15, v[228:231], s[2:3] offset:16
	s_ashr_i32 s1, s0, 31
	s_lshl_b64 s[2:3], s[0:1], 13
	s_add_u32 s2, s7, s2
	s_addc_u32 s3, s6, s3
	s_add_i32 s0, s0, s80
	s_waitcnt vmcnt(45)
	v_fmamk_f32 v220, v50, 0x3a000000, v0
	v_mul_f32_e32 v221, 0x4b800000, v220
	v_cmp_gt_f32_e32 vcc, s4, v220
	s_nop 1
	v_cndmask_b32_e32 v220, v220, v221, vcc
	v_rsq_f32_e32 v218, v220
	s_nop 0
	v_mul_f32_e32 v221, 0x45800000, v218
	v_cndmask_b32_e32 v218, v218, v221, vcc
	s_waitcnt vmcnt(44)
	v_lshlrev_b32_e32 v200, 16, v96
	v_and_b32_e32 v201, 0xffff0000, v96
	v_lshlrev_b32_e32 v202, 16, v97
	v_and_b32_e32 v203, 0xffff0000, v97
	v_lshlrev_b32_e32 v204, 16, v98
	v_and_b32_e32 v205, 0xffff0000, v98
	v_lshlrev_b32_e32 v206, 16, v99
	v_and_b32_e32 v207, 0xffff0000, v99
	v_pk_mul_f32 v[200:201], v[218:219], v[200:201] op_sel_hi:[0,1]
	v_pk_mul_f32 v[202:203], v[218:219], v[202:203] op_sel_hi:[0,1]
	v_pk_mul_f32 v[204:205], v[218:219], v[204:205] op_sel_hi:[0,1]
	v_pk_mul_f32 v[206:207], v[218:219], v[206:207] op_sel_hi:[0,1]
	v_pk_mul_f32 v[208:209], v[16:17], v[200:201]
	v_pk_mul_f32 v[210:211], v[18:19], v[202:203]
	v_pk_mul_f32 v[212:213], v[20:21], v[204:205]
	v_pk_mul_f32 v[214:215], v[22:23], v[206:207]
	global_store_dwordx4 v12, v[208:211], s[2:3]
	global_store_dwordx4 v12, v[212:215], s[2:3] offset:16
	s_waitcnt vmcnt(45)
	v_lshlrev_b32_e32 v200, 16, v100
	v_and_b32_e32 v201, 0xffff0000, v100
	v_lshlrev_b32_e32 v202, 16, v101
	v_and_b32_e32 v203, 0xffff0000, v101
	v_lshlrev_b32_e32 v204, 16, v102
	v_and_b32_e32 v205, 0xffff0000, v102
	v_lshlrev_b32_e32 v206, 16, v103
	v_and_b32_e32 v207, 0xffff0000, v103
	v_pk_mul_f32 v[200:201], v[218:219], v[200:201] op_sel_hi:[0,1]
	v_pk_mul_f32 v[202:203], v[218:219], v[202:203] op_sel_hi:[0,1]
	v_pk_mul_f32 v[204:205], v[218:219], v[204:205] op_sel_hi:[0,1]
	v_pk_mul_f32 v[206:207], v[218:219], v[206:207] op_sel_hi:[0,1]
	v_pk_mul_f32 v[224:225], v[24:25], v[200:201]
	v_pk_mul_f32 v[226:227], v[26:27], v[202:203]
	v_pk_mul_f32 v[228:229], v[28:29], v[204:205]
	v_pk_mul_f32 v[230:231], v[30:31], v[206:207]
	global_store_dwordx4 v13, v[224:227], s[2:3]
	global_store_dwordx4 v13, v[228:231], s[2:3] offset:16
	s_waitcnt vmcnt(46)
	v_lshlrev_b32_e32 v200, 16, v104
	v_and_b32_e32 v201, 0xffff0000, v104
	v_lshlrev_b32_e32 v202, 16, v105
	v_and_b32_e32 v203, 0xffff0000, v105
	v_lshlrev_b32_e32 v204, 16, v106
	v_and_b32_e32 v205, 0xffff0000, v106
	v_lshlrev_b32_e32 v206, 16, v107
	v_and_b32_e32 v207, 0xffff0000, v107
	v_pk_mul_f32 v[200:201], v[218:219], v[200:201] op_sel_hi:[0,1]
	v_pk_mul_f32 v[202:203], v[218:219], v[202:203] op_sel_hi:[0,1]
	v_pk_mul_f32 v[204:205], v[218:219], v[204:205] op_sel_hi:[0,1]
	v_pk_mul_f32 v[206:207], v[218:219], v[206:207] op_sel_hi:[0,1]
	v_pk_mul_f32 v[208:209], v[32:33], v[200:201]
	v_pk_mul_f32 v[210:211], v[34:35], v[202:203]
	v_pk_mul_f32 v[212:213], v[36:37], v[204:205]
	v_pk_mul_f32 v[214:215], v[38:39], v[206:207]
	global_store_dwordx4 v14, v[208:211], s[2:3]
	global_store_dwordx4 v14, v[212:215], s[2:3] offset:16
	s_waitcnt vmcnt(47)
	v_lshlrev_b32_e32 v200, 16, v108
	v_and_b32_e32 v201, 0xffff0000, v108
	v_lshlrev_b32_e32 v202, 16, v109
	v_and_b32_e32 v203, 0xffff0000, v109
	v_lshlrev_b32_e32 v204, 16, v110
	v_and_b32_e32 v205, 0xffff0000, v110
	v_lshlrev_b32_e32 v206, 16, v111
	v_and_b32_e32 v207, 0xffff0000, v111
	v_pk_mul_f32 v[200:201], v[218:219], v[200:201] op_sel_hi:[0,1]
	v_pk_mul_f32 v[202:203], v[218:219], v[202:203] op_sel_hi:[0,1]
	v_pk_mul_f32 v[204:205], v[218:219], v[204:205] op_sel_hi:[0,1]
	v_pk_mul_f32 v[206:207], v[218:219], v[206:207] op_sel_hi:[0,1]
	v_pk_mul_f32 v[224:225], v[40:41], v[200:201]
	v_pk_mul_f32 v[226:227], v[42:43], v[202:203]
	v_pk_mul_f32 v[228:229], v[44:45], v[204:205]
	v_pk_mul_f32 v[230:231], v[46:47], v[206:207]
	global_store_dwordx4 v15, v[224:227], s[2:3]
	global_store_dwordx4 v15, v[228:231], s[2:3] offset:16
	s_ashr_i32 s1, s0, 31
	s_lshl_b64 s[2:3], s[0:1], 13
	s_add_u32 s2, s7, s2
	s_addc_u32 s3, s6, s3
	s_add_i32 s0, s0, s80
	s_waitcnt vmcnt(48)
; __device__ __forceinline__ void unpack8(u32x4 r, float* f) { f[0] = bflo(r.x); f[1] = bfhi(r.x); f[2] = bflo(r.y); f[3] = bfhi(r.y); f[4] = bflo(r.z); f[5] = bfhi(r.z); f[6] = bflo(r.w); f[7] = bfhi(r.w); }
; __device__ __forceinline__ void phase_final(const PT& p, int lane, int wave) {
;     ...
;         const float rs = rsqrtf(st2[m] * (1.f / 2048.f) + EPS);
;         const u32x4* xr = (const u32x4*)(X2 + (size_t)m * 2048) + lane; f32x4* orow = (f32x4*)(p.out + (size_t)m * 2048);
; #pragma unroll
;         for (int j = 0; j < 4; ++j) {
;             float f[8]; unpack8(xr[64 * j], f); const int c = 8 * (lane + 64 * j);
;             const f32x4 g0 = *(const f32x4*)(g + c), g1 = *(const f32x4*)(g + c + 4);
;             orow[(c >> 2)] = (f32x4){f[0] * rs * g0.x, f[1] * rs * g0.y, f[2] * rs * g0.z, f[3] * rs * g0.w};
;             orow[(c >> 2) + 1] = (f32x4){f[4] * rs * g1.x, f[5] * rs * g1.y, f[6] * rs * g1.z, f[7] * rs * g1.w};
	v_fmamk_f32 v220, v51, 0x3a000000, v0
	v_mul_f32_e32 v221, 0x4b800000, v220
	v_cmp_gt_f32_e32 vcc, s4, v220
	s_nop 1
	v_cndmask_b32_e32 v220, v220, v221, vcc
	v_rsq_f32_e32 v218, v220
	s_nop 0
	v_mul_f32_e32 v221, 0x45800000, v218
	v_cndmask_b32_e32 v218, v218, v221, vcc
	s_waitcnt vmcnt(47)
	v_lshlrev_b32_e32 v200, 16, v112
	v_and_b32_e32 v201, 0xffff0000, v112
	v_lshlrev_b32_e32 v202, 16, v113
	v_and_b32_e32 v203, 0xffff0000, v113
	v_lshlrev_b32_e32 v204, 16, v114
	v_and_b32_e32 v205, 0xffff0000, v114
	v_lshlrev_b32_e32 v206, 16, v115
	v_and_b32_e32 v207, 0xffff0000, v115
	v_pk_mul_f32 v[200:201], v[218:219], v[200:201] op_sel_hi:[0,1]
	v_pk_mul_f32 v[202:203], v[218:219], v[202:203] op_sel_hi:[0,1]
	v_pk_mul_f32 v[204:205], v[218:219], v[204:205] op_sel_hi:[0,1]
	v_pk_mul_f32 v[206:207], v[218:219], v[206:207] op_sel_hi:[0,1]
	v_pk_mul_f32 v[208:209], v[16:17], v[200:201]
	v_pk_mul_f32 v[210:211], v[18:19], v[202:203]
	v_pk_mul_f32 v[212:213], v[20:21], v[204:205]
	v_pk_mul_f32 v[214:215], v[22:23], v[206:207]
	global_store_dwordx4 v12, v[208:211], s[2:3]
	global_store_dwordx4 v12, v[212:215], s[2:3] offset:16
	s_waitcnt vmcnt(48)
	v_lshlrev_b32_e32 v200, 16, v116
	v_and_b32_e32 v201, 0xffff0000, v116
	v_lshlrev_b32_e32 v202, 16, v117
	v_and_b32_e32 v203, 0xffff0000, v117
	v_lshlrev_b32_e32 v204, 16, v118
	v_and_b32_e32 v205, 0xffff0000, v118
	v_lshlrev_b32_e32 v206, 16, v119
	v_and_b32_e32 v207, 0xffff0000, v119
	v_pk_mul_f32 v[200:201], v[218:219], v[200:201] op_sel_hi:[0,1]
	v_pk_mul_f32 v[202:203], v[218:219], v[202:203] op_sel_hi:[0,1]
	v_pk_mul_f32 v[204:205], v[218:219], v[204:205] op_sel_hi:[0,1]
	v_pk_mul_f32 v[206:207], v[218:219], v[206:207] op_sel_hi:[0,1]
	v_pk_mul_f32 v[224:225], v[24:25], v[200:201]
	v_pk_mul_f32 v[226:227], v[26:27], v[202:203]
	v_pk_mul_f32 v[228:229], v[28:29], v[204:205]
	v_pk_mul_f32 v[230:231], v[30:31], v[206:207]
	global_store_dwordx4 v13, v[224:227], s[2:3]
	global_store_dwordx4 v13, v[228:231], s[2:3] offset:16
	s_waitcnt vmcnt(49)
	v_lshlrev_b32_e32 v200, 16, v120
	v_and_b32_e32 v201, 0xffff0000, v120
	v_lshlrev_b32_e32 v202, 16, v121
	v_and_b32_e32 v203, 0xffff0000, v121
	v_lshlrev_b32_e32 v204, 16, v122
	v_and_b32_e32 v205, 0xffff0000, v122
	v_lshlrev_b32_e32 v206, 16, v123
	v_and_b32_e32 v207, 0xffff0000, v123
	v_pk_mul_f32 v[200:201], v[218:219], v[200:201] op_sel_hi:[0,1]
	v_pk_mul_f32 v[202:203], v[218:219], v[202:203] op_sel_hi:[0,1]
	v_pk_mul_f32 v[204:205], v[218:219], v[204:205] op_sel_hi:[0,1]
	v_pk_mul_f32 v[206:207], v[218:219], v[206:207] op_sel_hi:[0,1]
	v_pk_mul_f32 v[208:209], v[32:33], v[200:201]
	v_pk_mul_f32 v[210:211], v[34:35], v[202:203]
	v_pk_mul_f32 v[212:213], v[36:37], v[204:205]
	v_pk_mul_f32 v[214:215], v[38:39], v[206:207]
	global_store_dwordx4 v14, v[208:211], s[2:3]
	global_store_dwordx4 v14, v[212:215], s[2:3] offset:16
	s_waitcnt vmcnt(50)
	v_lshlrev_b32_e32 v200, 16, v124
	v_and_b32_e32 v201, 0xffff0000, v124
	v_lshlrev_b32_e32 v202, 16, v125
	v_and_b32_e32 v203, 0xffff0000, v125
	v_lshlrev_b32_e32 v204, 16, v126
	v_and_b32_e32 v205, 0xffff0000, v126
	v_lshlrev_b32_e32 v206, 16, v127
	v_and_b32_e32 v207, 0xffff0000, v127
	v_pk_mul_f32 v[200:201], v[218:219], v[200:201] op_sel_hi:[0,1]
	v_pk_mul_f32 v[202:203], v[218:219], v[202:203] op_sel_hi:[0,1]
	v_pk_mul_f32 v[204:205], v[218:219], v[204:205] op_sel_hi:[0,1]
	v_pk_mul_f32 v[206:207], v[218:219], v[206:207] op_sel_hi:[0,1]
	v_pk_mul_f32 v[224:225], v[40:41], v[200:201]
	v_pk_mul_f32 v[226:227], v[42:43], v[202:203]
	v_pk_mul_f32 v[228:229], v[44:45], v[204:205]
	v_pk_mul_f32 v[230:231], v[46:47], v[206:207]
	global_store_dwordx4 v15, v[224:227], s[2:3]
	global_store_dwordx4 v15, v[228:231], s[2:3] offset:16
	s_ashr_i32 s1, s0, 31
	s_lshl_b64 s[2:3], s[0:1], 13
	s_add_u32 s2, s7, s2
	s_addc_u32 s3, s6, s3
	s_add_i32 s0, s0, s80
	s_waitcnt vmcnt(51)
	v_fmamk_f32 v220, v52, 0x3a000000, v0
	v_mul_f32_e32 v221, 0x4b800000, v220
	v_cmp_gt_f32_e32 vcc, s4, v220
	s_nop 1
	v_cndmask_b32_e32 v220, v220, v221, vcc
	v_rsq_f32_e32 v218, v220
	s_nop 0
	v_mul_f32_e32 v221, 0x45800000, v218
	v_cndmask_b32_e32 v218, v218, v221, vcc
	s_waitcnt vmcnt(50)
	v_lshlrev_b32_e32 v200, 16, v128
	v_and_b32_e32 v201, 0xffff0000, v128
	v_lshlrev_b32_e32 v202, 16, v129
	v_and_b32_e32 v203, 0xffff0000, v129
	v_lshlrev_b32_e32 v204, 16, v130
	v_and_b32_e32 v205, 0xffff0000, v130
	v_lshlrev_b32_e32 v206, 16, v131
	v_and_b32_e32 v207, 0xffff0000, v131
	v_pk_mul_f32 v[200:201], v[218:219], v[200:201] op_sel_hi:[0,1]
	v_pk_mul_f32 v[202:203], v[218:219], v[202:203] op_sel_hi:[0,1]
	v_pk_mul_f32 v[204:205], v[218:219], v[204:205] op_sel_hi:[0,1]
	v_pk_mul_f32 v[206:207], v[218:219], v[206:207] op_sel_hi:[0,1]
	v_pk_mul_f32 v[208:209], v[16:17], v[200:201]
	v_pk_mul_f32 v[210:211], v[18:19], v[202:203]
	v_pk_mul_f32 v[212:213], v[20:21], v[204:205]
	v_pk_mul_f32 v[214:215], v[22:23], v[206:207]
	global_store_dwordx4 v12, v[208:211], s[2:3]
	global_store_dwordx4 v12, v[212:215], s[2:3] offset:16
	s_waitcnt vmcnt(51)
	v_lshlrev_b32_e32 v200, 16, v132
	v_and_b32_e32 v201, 0xffff0000, v132
	v_lshlrev_b32_e32 v202, 16, v133
	v_and_b32_e32 v203, 0xffff0000, v133
	v_lshlrev_b32_e32 v204, 16, v134
	v_and_b32_e32 v205, 0xffff0000, v134
	v_lshlrev_b32_e32 v206, 16, v135
	v_and_b32_e32 v207, 0xffff0000, v135
	v_pk_mul_f32 v[200:201], v[218:219], v[200:201] op_sel_hi:[0,1]
	v_pk_mul_f32 v[202:203], v[218:219], v[202:203] op_sel_hi:[0,1]
	v_pk_mul_f32 v[204:205], v[218:219], v[204:205] op_sel_hi:[0,1]
	v_pk_mul_f32 v[206:207], v[218:219], v[206:207] op_sel_hi:[0,1]
	v_pk_mul_f32 v[224:225], v[24:25], v[200:201]
	v_pk_mul_f32 v[226:227], v[26:27], v[202:203]
	v_pk_mul_f32 v[228:229], v[28:29], v[204:205]
	v_pk_mul_f32 v[230:231], v[30:31], v[206:207]
	global_store_dwordx4 v13, v[224:227], s[2:3]
	global_store_dwordx4 v13, v[228:231], s[2:3] offset:16
	s_waitcnt vmcnt(52)
; __device__ __forceinline__ void unpack8(u32x4 r, float* f) { f[0] = bflo(r.x); f[1] = bfhi(r.x); f[2] = bflo(r.y); f[3] = bfhi(r.y); f[4] = bflo(r.z); f[5] = bfhi(r.z); f[6] = bflo(r.w); f[7] = bfhi(r.w); }
; __device__ __forceinline__ void phase_final(const PT& p, int lane, int wave) {
;     ...
;         const float rs = rsqrtf(st2[m] * (1.f / 2048.f) + EPS);
;         const u32x4* xr = (const u32x4*)(X2 + (size_t)m * 2048) + lane; f32x4* orow = (f32x4*)(p.out + (size_t)m * 2048);
; #pragma unroll
;         for (int j = 0; j < 4; ++j) {
;             float f[8]; unpack8(xr[64 * j], f); const int c = 8 * (lane + 64 * j);
;             const f32x4 g0 = *(const f32x4*)(g + c), g1 = *(const f32x4*)(g + c + 4);
;             orow[(c >> 2)] = (f32x4){f[0] * rs * g0.x, f[1] * rs * g0.y, f[2] * rs * g0.z, f[3] * rs * g0.w};
;             orow[(c >> 2) + 1] = (f32x4){f[4] * rs * g1.x, f[5] * rs * g1.y, f[6] * rs * g1.z, f[7] * rs * g1.w};
	v_lshlrev_b32_e32 v200, 16, v136
	v_and_b32_e32 v201, 0xffff0000, v136
	v_lshlrev_b32_e32 v202, 16, v137
	v_and_b32_e32 v203, 0xffff0000, v137
	v_lshlrev_b32_e32 v204, 16, v138
	v_and_b32_e32 v205, 0xffff0000, v138
	v_lshlrev_b32_e32 v206, 16, v139
	v_and_b32_e32 v207, 0xffff0000, v139
	v_pk_mul_f32 v[200:201], v[218:219], v[200:201] op_sel_hi:[0,1]
	v_pk_mul_f32 v[202:203], v[218:219], v[202:203] op_sel_hi:[0,1]
	v_pk_mul_f32 v[204:205], v[218:219], v[204:205] op_sel_hi:[0,1]
	v_pk_mul_f32 v[206:207], v[218:219], v[206:207] op_sel_hi:[0,1]
	v_pk_mul_f32 v[208:209], v[32:33], v[200:201]
	v_pk_mul_f32 v[210:211], v[34:35], v[202:203]
	v_pk_mul_f32 v[212:213], v[36:37], v[204:205]
	v_pk_mul_f32 v[214:215], v[38:39], v[206:207]
	global_store_dwordx4 v14, v[208:211], s[2:3]
	global_store_dwordx4 v14, v[212:215], s[2:3] offset:16
	s_waitcnt vmcnt(53)
	v_lshlrev_b32_e32 v200, 16, v140
	v_and_b32_e32 v201, 0xffff0000, v140
	v_lshlrev_b32_e32 v202, 16, v141
	v_and_b32_e32 v203, 0xffff0000, v141
	v_lshlrev_b32_e32 v204, 16, v142
	v_and_b32_e32 v205, 0xffff0000, v142
	v_lshlrev_b32_e32 v206, 16, v143
	v_and_b32_e32 v207, 0xffff0000, v143
	v_pk_mul_f32 v[200:201], v[218:219], v[200:201] op_sel_hi:[0,1]
	v_pk_mul_f32 v[202:203], v[218:219], v[202:203] op_sel_hi:[0,1]
	v_pk_mul_f32 v[204:205], v[218:219], v[204:205] op_sel_hi:[0,1]
	v_pk_mul_f32 v[206:207], v[218:219], v[206:207] op_sel_hi:[0,1]
	v_pk_mul_f32 v[224:225], v[40:41], v[200:201]
	v_pk_mul_f32 v[226:227], v[42:43], v[202:203]
	v_pk_mul_f32 v[228:229], v[44:45], v[204:205]
	v_pk_mul_f32 v[230:231], v[46:47], v[206:207]
	global_store_dwordx4 v15, v[224:227], s[2:3]
	global_store_dwordx4 v15, v[228:231], s[2:3] offset:16
	s_ashr_i32 s1, s0, 31
	s_lshl_b64 s[2:3], s[0:1], 13
	s_add_u32 s2, s7, s2
	s_addc_u32 s3, s6, s3
	s_add_i32 s0, s0, s80
	s_waitcnt vmcnt(54)
	v_fmamk_f32 v220, v53, 0x3a000000, v0
	v_mul_f32_e32 v221, 0x4b800000, v220
	v_cmp_gt_f32_e32 vcc, s4, v220
	s_nop 1
	v_cndmask_b32_e32 v220, v220, v221, vcc
	v_rsq_f32_e32 v218, v220
	s_nop 0
	v_mul_f32_e32 v221, 0x45800000, v218
	v_cndmask_b32_e32 v218, v218, v221, vcc
	s_waitcnt vmcnt(53)
	v_lshlrev_b32_e32 v200, 16, v144
	v_and_b32_e32 v201, 0xffff0000, v144
	v_lshlrev_b32_e32 v202, 16, v145
	v_and_b32_e32 v203, 0xffff0000, v145
	v_lshlrev_b32_e32 v204, 16, v146
	v_and_b32_e32 v205, 0xffff0000, v146
	v_lshlrev_b32_e32 v206, 16, v147
	v_and_b32_e32 v207, 0xffff0000, v147
	v_pk_mul_f32 v[200:201], v[218:219], v[200:201] op_sel_hi:[0,1]
	v_pk_mul_f32 v[202:203], v[218:219], v[202:203] op_sel_hi:[0,1]
	v_pk_mul_f32 v[204:205], v[218:219], v[204:205] op_sel_hi:[0,1]
	v_pk_mul_f32 v[206:207], v[218:219], v[206:207] op_sel_hi:[0,1]
	v_pk_mul_f32 v[208:209], v[16:17], v[200:201]
	v_pk_mul_f32 v[210:211], v[18:19], v[202:203]
	v_pk_mul_f32 v[212:213], v[20:21], v[204:205]
	v_pk_mul_f32 v[214:215], v[22:23], v[206:207]
	global_store_dwordx4 v12, v[208:211], s[2:3]
	global_store_dwordx4 v12, v[212:215], s[2:3] offset:16
	s_waitcnt vmcnt(54)
	v_lshlrev_b32_e32 v200, 16, v148
	v_and_b32_e32 v201, 0xffff0000, v148
	v_lshlrev_b32_e32 v202, 16, v149
	v_and_b32_e32 v203, 0xffff0000, v149
	v_lshlrev_b32_e32 v204, 16, v150
	v_and_b32_e32 v205, 0xffff0000, v150
	v_lshlrev_b32_e32 v206, 16, v151
	v_and_b32_e32 v207, 0xffff0000, v151
	v_pk_mul_f32 v[200:201], v[218:219], v[200:201] op_sel_hi:[0,1]
	v_pk_mul_f32 v[202:203], v[218:219], v[202:203] op_sel_hi:[0,1]
	v_pk_mul_f32 v[204:205], v[218:219], v[204:205] op_sel_hi:[0,1]
	v_pk_mul_f32 v[206:207], v[218:219], v[206:207] op_sel_hi:[0,1]
	v_pk_mul_f32 v[224:225], v[24:25], v[200:201]
	v_pk_mul_f32 v[226:227], v[26:27], v[202:203]
	v_pk_mul_f32 v[228:229], v[28:29], v[204:205]
	v_pk_mul_f32 v[230:231], v[30:31], v[206:207]
	global_store_dwordx4 v13, v[224:227], s[2:3]
	global_store_dwordx4 v13, v[228:231], s[2:3] offset:16
	s_waitcnt vmcnt(55)
	v_lshlrev_b32_e32 v200, 16, v152
	v_and_b32_e32 v201, 0xffff0000, v152
	v_lshlrev_b32_e32 v202, 16, v153
	v_and_b32_e32 v203, 0xffff0000, v153
	v_lshlrev_b32_e32 v204, 16, v154
	v_and_b32_e32 v205, 0xffff0000, v154
	v_lshlrev_b32_e32 v206, 16, v155
	v_and_b32_e32 v207, 0xffff0000, v155
	v_pk_mul_f32 v[200:201], v[218:219], v[200:201] op_sel_hi:[0,1]
	v_pk_mul_f32 v[202:203], v[218:219], v[202:203] op_sel_hi:[0,1]
	v_pk_mul_f32 v[204:205], v[218:219], v[204:205] op_sel_hi:[0,1]
	v_pk_mul_f32 v[206:207], v[218:219], v[206:207] op_sel_hi:[0,1]
	v_pk_mul_f32 v[208:209], v[32:33], v[200:201]
	v_pk_mul_f32 v[210:211], v[34:35], v[202:203]
	v_pk_mul_f32 v[212:213], v[36:37], v[204:205]
	v_pk_mul_f32 v[214:215], v[38:39], v[206:207]
	global_store_dwordx4 v14, v[208:211], s[2:3]
	global_store_dwordx4 v14, v[212:215], s[2:3] offset:16
	s_waitcnt vmcnt(56)
	v_lshlrev_b32_e32 v200, 16, v156
	v_and_b32_e32 v201, 0xffff0000, v156
	v_lshlrev_b32_e32 v202, 16, v157
	v_and_b32_e32 v203, 0xffff0000, v157
	v_lshlrev_b32_e32 v204, 16, v158
	v_and_b32_e32 v205, 0xffff0000, v158
	v_lshlrev_b32_e32 v206, 16, v159
	v_and_b32_e32 v207, 0xffff0000, v159
	v_pk_mul_f32 v[200:201], v[218:219], v[200:201] op_sel_hi:[0,1]
	v_pk_mul_f32 v[202:203], v[218:219], v[202:203] op_sel_hi:[0,1]
	v_pk_mul_f32 v[204:205], v[218:219], v[204:205] op_sel_hi:[0,1]
	v_pk_mul_f32 v[206:207], v[218:219], v[206:207] op_sel_hi:[0,1]
	v_pk_mul_f32 v[224:225], v[40:41], v[200:201]
	v_pk_mul_f32 v[226:227], v[42:43], v[202:203]
	v_pk_mul_f32 v[228:229], v[44:45], v[204:205]
	v_pk_mul_f32 v[230:231], v[46:47], v[206:207]
	global_store_dwordx4 v15, v[224:227], s[2:3]
	global_store_dwordx4 v15, v[228:231], s[2:3] offset:16
	s_ashr_i32 s1, s0, 31
	s_lshl_b64 s[2:3], s[0:1], 13
	s_add_u32 s2, s7, s2
	s_addc_u32 s3, s6, s3
	s_add_i32 s0, s0, s80
	s_waitcnt vmcnt(57)
; __device__ __forceinline__ void unpack8(u32x4 r, float* f) { f[0] = bflo(r.x); f[1] = bfhi(r.x); f[2] = bflo(r.y); f[3] = bfhi(r.y); f[4] = bflo(r.z); f[5] = bfhi(r.z); f[6] = bflo(r.w); f[7] = bfhi(r.w); }
; __device__ __forceinline__ void phase_final(const PT& p, int lane, int wave) {
;     ...
;         const float rs = rsqrtf(st2[m] * (1.f / 2048.f) + EPS);
;         const u32x4* xr = (const u32x4*)(X2 + (size_t)m * 2048) + lane; f32x4* orow = (f32x4*)(p.out + (size_t)m * 2048);
; #pragma unroll
;         for (int j = 0; j < 4; ++j) {
;             float f[8]; unpack8(xr[64 * j], f); const int c = 8 * (lane + 64 * j);
;             const f32x4 g0 = *(const f32x4*)(g + c), g1 = *(const f32x4*)(g + c + 4);
;             orow[(c >> 2)] = (f32x4){f[0] * rs * g0.x, f[1] * rs * g0.y, f[2] * rs * g0.z, f[3] * rs * g0.w};
;             orow[(c >> 2) + 1] = (f32x4){f[4] * rs * g1.x, f[5] * rs * g1.y, f[6] * rs * g1.z, f[7] * rs * g1.w};
	v_fmamk_f32 v220, v54, 0x3a000000, v0
	v_mul_f32_e32 v221, 0x4b800000, v220
	v_cmp_gt_f32_e32 vcc, s4, v220
	s_nop 1
	v_cndmask_b32_e32 v220, v220, v221, vcc
	v_rsq_f32_e32 v218, v220
	s_nop 0
	v_mul_f32_e32 v221, 0x45800000, v218
	v_cndmask_b32_e32 v218, v218, v221, vcc
	s_waitcnt vmcnt(56)
	v_lshlrev_b32_e32 v200, 16, v160
	v_and_b32_e32 v201, 0xffff0000, v160
	v_lshlrev_b32_e32 v202, 16, v161
	v_and_b32_e32 v203, 0xffff0000, v161
	v_lshlrev_b32_e32 v204, 16, v162
	v_and_b32_e32 v205, 0xffff0000, v162
	v_lshlrev_b32_e32 v206, 16, v163
	v_and_b32_e32 v207, 0xffff0000, v163
	v_pk_mul_f32 v[200:201], v[218:219], v[200:201] op_sel_hi:[0,1]
	v_pk_mul_f32 v[202:203], v[218:219], v[202:203] op_sel_hi:[0,1]
	v_pk_mul_f32 v[204:205], v[218:219], v[204:205] op_sel_hi:[0,1]
	v_pk_mul_f32 v[206:207], v[218:219], v[206:207] op_sel_hi:[0,1]
	v_pk_mul_f32 v[208:209], v[16:17], v[200:201]
	v_pk_mul_f32 v[210:211], v[18:19], v[202:203]
	v_pk_mul_f32 v[212:213], v[20:21], v[204:205]
	v_pk_mul_f32 v[214:215], v[22:23], v[206:207]
	global_store_dwordx4 v12, v[208:211], s[2:3]
	global_store_dwordx4 v12, v[212:215], s[2:3] offset:16
	s_waitcnt vmcnt(57)
	v_lshlrev_b32_e32 v200, 16, v164
	v_and_b32_e32 v201, 0xffff0000, v164
	v_lshlrev_b32_e32 v202, 16, v165
	v_and_b32_e32 v203, 0xffff0000, v165
	v_lshlrev_b32_e32 v204, 16, v166
	v_and_b32_e32 v205, 0xffff0000, v166
	v_lshlrev_b32_e32 v206, 16, v167
	v_and_b32_e32 v207, 0xffff0000, v167
	v_pk_mul_f32 v[200:201], v[218:219], v[200:201] op_sel_hi:[0,1]
	v_pk_mul_f32 v[202:203], v[218:219], v[202:203] op_sel_hi:[0,1]
	v_pk_mul_f32 v[204:205], v[218:219], v[204:205] op_sel_hi:[0,1]
	v_pk_mul_f32 v[206:207], v[218:219], v[206:207] op_sel_hi:[0,1]
	v_pk_mul_f32 v[224:225], v[24:25], v[200:201]
	v_pk_mul_f32 v[226:227], v[26:27], v[202:203]
	v_pk_mul_f32 v[228:229], v[28:29], v[204:205]
	v_pk_mul_f32 v[230:231], v[30:31], v[206:207]
	global_store_dwordx4 v13, v[224:227], s[2:3]
	global_store_dwordx4 v13, v[228:231], s[2:3] offset:16
	s_waitcnt vmcnt(58)
	v_lshlrev_b32_e32 v200, 16, v168
	v_and_b32_e32 v201, 0xffff0000, v168
	v_lshlrev_b32_e32 v202, 16, v169
	v_and_b32_e32 v203, 0xffff0000, v169
	v_lshlrev_b32_e32 v204, 16, v170
	v_and_b32_e32 v205, 0xffff0000, v170
	v_lshlrev_b32_e32 v206, 16, v171
	v_and_b32_e32 v207, 0xffff0000, v171
	v_pk_mul_f32 v[200:201], v[218:219], v[200:201] op_sel_hi:[0,1]
	v_pk_mul_f32 v[202:203], v[218:219], v[202:203] op_sel_hi:[0,1]
	v_pk_mul_f32 v[204:205], v[218:219], v[204:205] op_sel_hi:[0,1]
	v_pk_mul_f32 v[206:207], v[218:219], v[206:207] op_sel_hi:[0,1]
	v_pk_mul_f32 v[208:209], v[32:33], v[200:201]
	v_pk_mul_f32 v[210:211], v[34:35], v[202:203]
	v_pk_mul_f32 v[212:213], v[36:37], v[204:205]
	v_pk_mul_f32 v[214:215], v[38:39], v[206:207]
	global_store_dwordx4 v14, v[208:211], s[2:3]
	global_store_dwordx4 v14, v[212:215], s[2:3] offset:16
	s_waitcnt vmcnt(59)
	v_lshlrev_b32_e32 v200, 16, v172
	v_and_b32_e32 v201, 0xffff0000, v172
	v_lshlrev_b32_e32 v202, 16, v173
	v_and_b32_e32 v203, 0xffff0000, v173
	v_lshlrev_b32_e32 v204, 16, v174
	v_and_b32_e32 v205, 0xffff0000, v174
	v_lshlrev_b32_e32 v206, 16, v175
	v_and_b32_e32 v207, 0xffff0000, v175
	v_pk_mul_f32 v[200:201], v[218:219], v[200:201] op_sel_hi:[0,1]
	v_pk_mul_f32 v[202:203], v[218:219], v[202:203] op_sel_hi:[0,1]
	v_pk_mul_f32 v[204:205], v[218:219], v[204:205] op_sel_hi:[0,1]
	v_pk_mul_f32 v[206:207], v[218:219], v[206:207] op_sel_hi:[0,1]
	v_pk_mul_f32 v[224:225], v[40:41], v[200:201]
	v_pk_mul_f32 v[226:227], v[42:43], v[202:203]
	v_pk_mul_f32 v[228:229], v[44:45], v[204:205]
	v_pk_mul_f32 v[230:231], v[46:47], v[206:207]
	global_store_dwordx4 v15, v[224:227], s[2:3]
	global_store_dwordx4 v15, v[228:231], s[2:3] offset:16
	s_ashr_i32 s1, s0, 31
	s_lshl_b64 s[2:3], s[0:1], 13
	s_add_u32 s2, s7, s2
	s_addc_u32 s3, s6, s3
	s_add_i32 s0, s0, s80
	s_waitcnt vmcnt(60)
; __device__ __forceinline__ void unpack8(u32x4 r, float* f) { f[0] = bflo(r.x); f[1] = bfhi(r.x); f[2] = bflo(r.y); f[3] = bfhi(r.y); f[4] = bflo(r.z); f[5] = bfhi(r.z); f[6] = bflo(r.w); f[7] = bfhi(r.w); }
; __device__ __forceinline__ void phase_final(const PT& p, int lane, int wave) {
;     ...
;         const float rs = rsqrtf(st2[m] * (1.f / 2048.f) + EPS);
;         const u32x4* xr = (const u32x4*)(X2 + (size_t)m * 2048) + lane; f32x4* orow = (f32x4*)(p.out + (size_t)m * 2048);
; #pragma unroll
;         for (int j = 0; j < 4; ++j) {
;             float f[8]; unpack8(xr[64 * j], f); const int c = 8 * (lane + 64 * j);
;             const f32x4 g0 = *(const f32x4*)(g + c), g1 = *(const f32x4*)(g + c + 4);
;             orow[(c >> 2)] = (f32x4){f[0] * rs * g0.x, f[1] * rs * g0.y, f[2] * rs * g0.z, f[3] * rs * g0.w};
;             orow[(c >> 2) + 1] = (f32x4){f[4] * rs * g1.x, f[5] * rs * g1.y, f[6] * rs * g1.z, f[7] * rs * g1.w};
	v_fmamk_f32 v220, v55, 0x3a000000, v0
	v_mul_f32_e32 v221, 0x4b800000, v220
	v_cmp_gt_f32_e32 vcc, s4, v220
	s_nop 1
	v_cndmask_b32_e32 v220, v220, v221, vcc
	v_rsq_f32_e32 v218, v220
	s_nop 0
	v_mul_f32_e32 v221, 0x45800000, v218
	v_cndmask_b32_e32 v218, v218, v221, vcc
	s_waitcnt vmcnt(59)
	v_lshlrev_b32_e32 v200, 16, v176
	v_and_b32_e32 v201, 0xffff0000, v176
	v_lshlrev_b32_e32 v202, 16, v177
	v_and_b32_e32 v203, 0xffff0000, v177
	v_lshlrev_b32_e32 v204, 16, v178
	v_and_b32_e32 v205, 0xffff0000, v178
	v_lshlrev_b32_e32 v206, 16, v179
	v_and_b32_e32 v207, 0xffff0000, v179
	v_pk_mul_f32 v[200:201], v[218:219], v[200:201] op_sel_hi:[0,1]
	v_pk_mul_f32 v[202:203], v[218:219], v[202:203] op_sel_hi:[0,1]
	v_pk_mul_f32 v[204:205], v[218:219], v[204:205] op_sel_hi:[0,1]
	v_pk_mul_f32 v[206:207], v[218:219], v[206:207] op_sel_hi:[0,1]
	v_pk_mul_f32 v[208:209], v[16:17], v[200:201]
	v_pk_mul_f32 v[210:211], v[18:19], v[202:203]
	v_pk_mul_f32 v[212:213], v[20:21], v[204:205]
	v_pk_mul_f32 v[214:215], v[22:23], v[206:207]
	global_store_dwordx4 v12, v[208:211], s[2:3]
	global_store_dwordx4 v12, v[212:215], s[2:3] offset:16
	s_waitcnt vmcnt(60)
	v_lshlrev_b32_e32 v200, 16, v180
	v_and_b32_e32 v201, 0xffff0000, v180
	v_lshlrev_b32_e32 v202, 16, v181
	v_and_b32_e32 v203, 0xffff0000, v181
	v_lshlrev_b32_e32 v204, 16, v182
	v_and_b32_e32 v205, 0xffff0000, v182
	v_lshlrev_b32_e32 v206, 16, v183
	v_and_b32_e32 v207, 0xffff0000, v183
	v_pk_mul_f32 v[200:201], v[218:219], v[200:201] op_sel_hi:[0,1]
	v_pk_mul_f32 v[202:203], v[218:219], v[202:203] op_sel_hi:[0,1]
	v_pk_mul_f32 v[204:205], v[218:219], v[204:205] op_sel_hi:[0,1]
	v_pk_mul_f32 v[206:207], v[218:219], v[206:207] op_sel_hi:[0,1]
	v_pk_mul_f32 v[224:225], v[24:25], v[200:201]
	v_pk_mul_f32 v[226:227], v[26:27], v[202:203]
	v_pk_mul_f32 v[228:229], v[28:29], v[204:205]
	v_pk_mul_f32 v[230:231], v[30:31], v[206:207]
	global_store_dwordx4 v13, v[224:227], s[2:3]
	global_store_dwordx4 v13, v[228:231], s[2:3] offset:16
	s_waitcnt vmcnt(61)
	v_lshlrev_b32_e32 v200, 16, v184
	v_and_b32_e32 v201, 0xffff0000, v184
	v_lshlrev_b32_e32 v202, 16, v185
	v_and_b32_e32 v203, 0xffff0000, v185
	v_lshlrev_b32_e32 v204, 16, v186
	v_and_b32_e32 v205, 0xffff0000, v186
	v_lshlrev_b32_e32 v206, 16, v187
	v_and_b32_e32 v207, 0xffff0000, v187
	v_pk_mul_f32 v[200:201], v[218:219], v[200:201] op_sel_hi:[0,1]
	v_pk_mul_f32 v[202:203], v[218:219], v[202:203] op_sel_hi:[0,1]
	v_pk_mul_f32 v[204:205], v[218:219], v[204:205] op_sel_hi:[0,1]
	v_pk_mul_f32 v[206:207], v[218:219], v[206:207] op_sel_hi:[0,1]
	v_pk_mul_f32 v[208:209], v[32:33], v[200:201]
	v_pk_mul_f32 v[210:211], v[34:35], v[202:203]
	v_pk_mul_f32 v[212:213], v[36:37], v[204:205]
	v_pk_mul_f32 v[214:215], v[38:39], v[206:207]
	global_store_dwordx4 v14, v[208:211], s[2:3]
	global_store_dwordx4 v14, v[212:215], s[2:3] offset:16
	s_waitcnt vmcnt(62)
	v_lshlrev_b32_e32 v200, 16, v188
	v_and_b32_e32 v201, 0xffff0000, v188
	v_lshlrev_b32_e32 v202, 16, v189
	v_and_b32_e32 v203, 0xffff0000, v189
	v_lshlrev_b32_e32 v204, 16, v190
	v_and_b32_e32 v205, 0xffff0000, v190
	v_lshlrev_b32_e32 v206, 16, v191
	v_and_b32_e32 v207, 0xffff0000, v191
	v_pk_mul_f32 v[200:201], v[218:219], v[200:201] op_sel_hi:[0,1]
	v_pk_mul_f32 v[202:203], v[218:219], v[202:203] op_sel_hi:[0,1]
	v_pk_mul_f32 v[204:205], v[218:219], v[204:205] op_sel_hi:[0,1]
	v_pk_mul_f32 v[206:207], v[218:219], v[206:207] op_sel_hi:[0,1]
	v_pk_mul_f32 v[224:225], v[40:41], v[200:201]
	v_pk_mul_f32 v[226:227], v[42:43], v[202:203]
	v_pk_mul_f32 v[228:229], v[44:45], v[204:205]
	v_pk_mul_f32 v[230:231], v[46:47], v[206:207]
	global_store_dwordx4 v15, v[224:227], s[2:3]
	global_store_dwordx4 v15, v[228:231], s[2:3] offset:16
